# RG-LRU depthwise conv rewritten: bias-initialised accumulators, per tap unpack + v_pk_fma_f32 over channel pairs under exec=row-in-range (outer taps), centre tap unmasked; same tap order, f32 fused ac
# speedup vs baseline: 1.0060x; 1.0060x over previous
.LBB0_264:
	s_and_b32 s65, s96, 63
	s_ashr_i32 s64, s20, 6
	s_lshl_b32 s4, s65, 8
	s_lshl_b32 s5, s64, 5
	v_and_b32_e32 v93, 31, v90
	s_add_i32 s12, s5, s4
	v_or_b32_e32 v9, s12, v93
	v_add_u32_e32 v0, -2, v9
	v_cmp_gt_u32_e32 vcc, s84, v0
	v_bfe_u32 v92, v90, 5, 1
	s_lshl_b32 s20, s73, 1
	v_cndmask_b32_e32 v2, v9, v0, vcc
	v_mov_b64_e32 v[0:1], s[52:53]
	v_mad_i64_i32 v[2:3], s[4:5], v2, s85, v[0:1]
	v_lshl_add_u64 v[2:3], v[2:3], 0, s[20:21]
	v_lshlrev_b32_e32 v88, 4, v92
	v_lshl_add_u64 v[4:5], v[2:3], 0, v[88:89]
	v_add_co_u32_e64 v2, s[4:5], s86, v4
	s_waitcnt lgkmcnt(0)
	s_nop 0
	v_addc_co_u32_e64 v3, s[4:5], 0, v5, s[4:5]
	s_barrier
	global_load_dwordx4 v[10:13], v[2:3], off offset:1024
	global_load_dwordx4 v[178:181], v[2:3], off offset:1056
	global_load_dwordx4 v[194:197], v[2:3], off offset:1088
	global_load_dwordx4 v[210:213], v[2:3], off offset:1120
	global_load_dwordx4 v[226:229], v[2:3], off offset:1152
	global_load_dwordx4 v[242:245], v[2:3], off offset:1184
	v_add_u32_e32 v2, -1, v9
	v_cmp_gt_u32_e64 s[4:5], s84, v2
	v_add_u32_e32 v18, 1, v9
	s_cmpk_lt_u32 s12, 0x4000
	v_cndmask_b32_e64 v2, v9, v2, s[4:5]
	v_mad_i64_i32 v[2:3], s[6:7], v2, s85, v[0:1]
	v_lshl_add_u64 v[2:3], v[2:3], 0, s[20:21]
	v_lshl_add_u64 v[2:3], v[2:3], 0, v[88:89]
	v_add_co_u32_e64 v6, s[6:7], s86, v2
	v_lshlrev_b32_e32 v91, 8, v93
	s_nop 0
	v_addc_co_u32_e64 v7, s[6:7], 0, v3, s[6:7]
	global_load_dwordx4 v[14:17], v[6:7], off offset:1024
	global_load_dwordx4 v[182:185], v[6:7], off offset:1056
	global_load_dwordx4 v[198:201], v[6:7], off offset:1088
	global_load_dwordx4 v[214:217], v[6:7], off offset:1120
	global_load_dwordx4 v[230:233], v[6:7], off offset:1152
	global_load_dwordx4 v[246:249], v[6:7], off offset:1184
	v_mad_i64_i32 v[6:7], s[6:7], v9, s85, v[0:1]
	v_cmp_gt_u32_e64 s[6:7], s84, v18
	v_lshl_add_u64 v[6:7], v[6:7], 0, s[20:21]
	v_lshl_add_u64 v[52:53], v[6:7], 0, v[88:89]
	v_cndmask_b32_e64 v9, v9, v18, s[6:7]
	v_mad_i64_i32 v[0:1], s[8:9], v9, s85, v[0:1]
	v_add_co_u32_e64 v6, s[8:9], s86, v52
	v_lshl_add_u64 v[0:1], v[0:1], 0, s[20:21]
	s_nop 0
	v_addc_co_u32_e64 v7, s[8:9], 0, v53, s[8:9]
	global_load_dwordx4 v[18:21], v[6:7], off offset:1024
	global_load_dwordx4 v[186:189], v[6:7], off offset:1056
	global_load_dwordx4 v[202:205], v[6:7], off offset:1088
	global_load_dwordx4 v[218:221], v[6:7], off offset:1120
	global_load_dwordx4 v[234:237], v[6:7], off offset:1152
	global_load_dwordx4 v[252:255], v[6:7], off offset:1184
	v_lshl_add_u64 v[6:7], v[0:1], 0, v[88:89]
	v_add_co_u32_e64 v0, s[8:9], s86, v6
	v_lshl_add_u32 v9, v92, 5, 16
	s_nop 0
	v_addc_co_u32_e64 v1, s[8:9], 0, v7, s[8:9]
	global_load_dwordx4 v[22:25], v[0:1], off offset:1024
	global_load_dwordx4 v[190:193], v[0:1], off offset:1056
	global_load_dwordx4 v[206:209], v[0:1], off offset:1088
	global_load_dwordx4 v[222:225], v[0:1], off offset:1120
	global_load_dwordx4 v[238:241], v[0:1], off offset:1152
	global_load_dwordx4 v[168:171], v[0:1], off offset:1184
	s_waitcnt vmcnt(26)
	s_waitcnt lgkmcnt(4)
	v_lshl_add_u64 v[0:1], v[4:5], 0, s[38:39]
	s_cselect_b64 s[8:9], -1, 0
	v_lshl_add_u64 v[6:7], v[6:7], 0, s[38:39]
	v_or_b32_e32 v138, s73, v93
	v_and_b32_e32 v8, 0x70, v8
	v_add_u32_e32 v94, 16, v91
	s_waitcnt vmcnt(23)
	s_waitcnt vmcnt(17)
	s_waitcnt lgkmcnt(3)
	s_waitcnt lgkmcnt(1)
	s_waitcnt lgkmcnt(0)
	s_waitcnt vmcnt(11)
	s_waitcnt vmcnt(5)
	ds_read_b128 v[26:29], v9 offset:10240
	ds_read_b128 v[30:33], v9 offset:10256
	ds_read_b128 v[34:37], v9 offset:8192
	ds_read_b128 v[38:41], v9 offset:8208
	ds_read_b128 v[42:45], v9 offset:8704
	ds_read_b128 v[80:83], v9 offset:8720
	s_mov_b64 exec, vcc
	v_lshlrev_b32_e32 v4, 16, v10
	v_and_b32_e32 v5, 0xffff0000, v10
	v_lshlrev_b32_e32 v46, 16, v11
	v_and_b32_e32 v47, 0xffff0000, v11
	s_waitcnt lgkmcnt(2)
	v_pk_fma_f32 v[26:27], v[34:35], v[4:5], v[26:27]
	v_pk_fma_f32 v[28:29], v[36:37], v[46:47], v[28:29]
	v_lshlrev_b32_e32 v84, 16, v12
	v_and_b32_e32 v85, 0xffff0000, v12
	v_lshlrev_b32_e32 v86, 16, v13
	v_and_b32_e32 v87, 0xffff0000, v13
	v_pk_fma_f32 v[30:31], v[38:39], v[84:85], v[30:31]
	v_pk_fma_f32 v[32:33], v[40:41], v[86:87], v[32:33]
	s_mov_b64 exec, -1
	ds_read_b128 v[34:37], v9 offset:9216
	ds_read_b128 v[38:41], v9 offset:9232
	s_mov_b64 exec, s[4:5]
	v_lshlrev_b32_e32 v4, 16, v14
	v_and_b32_e32 v5, 0xffff0000, v14
	v_lshlrev_b32_e32 v46, 16, v15
	v_and_b32_e32 v47, 0xffff0000, v15
	s_waitcnt lgkmcnt(2)
	v_pk_fma_f32 v[26:27], v[42:43], v[4:5], v[26:27]
	v_pk_fma_f32 v[28:29], v[44:45], v[46:47], v[28:29]
	v_lshlrev_b32_e32 v84, 16, v16
	v_and_b32_e32 v85, 0xffff0000, v16
	v_lshlrev_b32_e32 v86, 16, v17
	v_and_b32_e32 v87, 0xffff0000, v17
	v_pk_fma_f32 v[30:31], v[80:81], v[84:85], v[30:31]
	v_pk_fma_f32 v[32:33], v[82:83], v[86:87], v[32:33]
	s_mov_b64 exec, -1
	ds_read_b128 v[42:45], v9 offset:9728
	ds_read_b128 v[80:83], v9 offset:9744
	v_lshlrev_b32_e32 v4, 16, v18
	v_and_b32_e32 v5, 0xffff0000, v18
	v_lshlrev_b32_e32 v46, 16, v19
	v_and_b32_e32 v47, 0xffff0000, v19
	s_waitcnt lgkmcnt(2)
	v_pk_fma_f32 v[26:27], v[34:35], v[4:5], v[26:27]
	v_pk_fma_f32 v[28:29], v[36:37], v[46:47], v[28:29]
	v_lshlrev_b32_e32 v84, 16, v20
	v_and_b32_e32 v85, 0xffff0000, v20
	v_lshlrev_b32_e32 v86, 16, v21
	v_and_b32_e32 v87, 0xffff0000, v21
	v_pk_fma_f32 v[30:31], v[38:39], v[84:85], v[30:31]
	v_pk_fma_f32 v[32:33], v[40:41], v[86:87], v[32:33]
	s_mov_b64 exec, s[6:7]
	v_lshlrev_b32_e32 v4, 16, v22
	v_and_b32_e32 v5, 0xffff0000, v22
	v_lshlrev_b32_e32 v46, 16, v23
	v_and_b32_e32 v47, 0xffff0000, v23
	s_waitcnt lgkmcnt(0)
	v_pk_fma_f32 v[26:27], v[42:43], v[4:5], v[26:27]
	v_pk_fma_f32 v[28:29], v[44:45], v[46:47], v[28:29]
	v_lshlrev_b32_e32 v84, 16, v24
	v_and_b32_e32 v85, 0xffff0000, v24
	v_lshlrev_b32_e32 v86, 16, v25
	v_and_b32_e32 v87, 0xffff0000, v25
	v_pk_fma_f32 v[30:31], v[80:81], v[84:85], v[30:31]
	v_pk_fma_f32 v[32:33], v[82:83], v[86:87], v[32:33]
	s_mov_b64 exec, -1
	v_cvt_pk_bf16_f32 v48, v26, v27
	v_cvt_pk_bf16_f32 v49, v28, v29
	v_cvt_pk_bf16_f32 v50, v30, v31
	v_cvt_pk_bf16_f32 v51, v32, v33
	s_waitcnt lgkmcnt(3)
	s_waitcnt lgkmcnt(1)
	s_waitcnt lgkmcnt(0)
	s_nop 0
	v_lshl_add_u64 v[4:5], v[2:3], 0, s[38:39]
	v_lshl_add_u64 v[2:3], v[52:53], 0, s[38:39]
	s_waitcnt vmcnt(4)
	s_waitcnt vmcnt(4)
	s_waitcnt lgkmcnt(3)
	s_waitcnt lgkmcnt(1)
	s_waitcnt lgkmcnt(0)
	s_waitcnt vmcnt(4)
	ds_read_b128 v[26:29], v9 offset:10304
	ds_read_b128 v[30:33], v9 offset:10320
	ds_read_b128 v[34:37], v9 offset:8256
	ds_read_b128 v[38:41], v9 offset:8272
	ds_read_b128 v[42:45], v9 offset:8768
	ds_read_b128 v[80:83], v9 offset:8784
	s_mov_b64 exec, vcc
	v_lshlrev_b32_e32 v46, 16, v178
	v_and_b32_e32 v47, 0xffff0000, v178
	v_lshlrev_b32_e32 v84, 16, v179
	v_and_b32_e32 v85, 0xffff0000, v179
	s_waitcnt lgkmcnt(2)
	v_pk_fma_f32 v[26:27], v[34:35], v[46:47], v[26:27]
	v_pk_fma_f32 v[28:29], v[36:37], v[84:85], v[28:29]
	v_lshlrev_b32_e32 v86, 16, v180
	v_and_b32_e32 v87, 0xffff0000, v180
	v_lshlrev_b32_e32 v96, 16, v181
	v_and_b32_e32 v97, 0xffff0000, v181
	v_pk_fma_f32 v[30:31], v[38:39], v[86:87], v[30:31]
	v_pk_fma_f32 v[32:33], v[40:41], v[96:97], v[32:33]
	s_mov_b64 exec, -1
	ds_read_b128 v[34:37], v9 offset:9280
	ds_read_b128 v[38:41], v9 offset:9296
	s_mov_b64 exec, s[4:5]
	v_lshlrev_b32_e32 v46, 16, v182
	v_and_b32_e32 v47, 0xffff0000, v182
	v_lshlrev_b32_e32 v84, 16, v183
	v_and_b32_e32 v85, 0xffff0000, v183
	s_waitcnt lgkmcnt(2)
	v_pk_fma_f32 v[26:27], v[42:43], v[46:47], v[26:27]
	v_pk_fma_f32 v[28:29], v[44:45], v[84:85], v[28:29]
	v_lshlrev_b32_e32 v86, 16, v184
	v_and_b32_e32 v87, 0xffff0000, v184
	v_lshlrev_b32_e32 v96, 16, v185
	v_and_b32_e32 v97, 0xffff0000, v185
	v_pk_fma_f32 v[30:31], v[80:81], v[86:87], v[30:31]
	v_pk_fma_f32 v[32:33], v[82:83], v[96:97], v[32:33]
	s_mov_b64 exec, -1
	ds_read_b128 v[42:45], v9 offset:9792
	ds_read_b128 v[80:83], v9 offset:9808
	v_lshlrev_b32_e32 v46, 16, v186
	v_and_b32_e32 v47, 0xffff0000, v186
	v_lshlrev_b32_e32 v84, 16, v187
	v_and_b32_e32 v85, 0xffff0000, v187
	s_waitcnt lgkmcnt(2)
	v_pk_fma_f32 v[26:27], v[34:35], v[46:47], v[26:27]
	v_pk_fma_f32 v[28:29], v[36:37], v[84:85], v[28:29]
	v_lshlrev_b32_e32 v86, 16, v188
	v_and_b32_e32 v87, 0xffff0000, v188
	v_lshlrev_b32_e32 v96, 16, v189
	v_and_b32_e32 v97, 0xffff0000, v189
	v_pk_fma_f32 v[30:31], v[38:39], v[86:87], v[30:31]
	v_pk_fma_f32 v[32:33], v[40:41], v[96:97], v[32:33]
	s_mov_b64 exec, s[6:7]
	v_lshlrev_b32_e32 v46, 16, v190
	v_and_b32_e32 v47, 0xffff0000, v190
	v_lshlrev_b32_e32 v84, 16, v191
	v_and_b32_e32 v85, 0xffff0000, v191
	s_waitcnt lgkmcnt(0)
	v_pk_fma_f32 v[26:27], v[42:43], v[46:47], v[26:27]
	v_pk_fma_f32 v[28:29], v[44:45], v[84:85], v[28:29]
	v_lshlrev_b32_e32 v86, 16, v192
	v_and_b32_e32 v87, 0xffff0000, v192
	v_lshlrev_b32_e32 v96, 16, v193
	v_and_b32_e32 v97, 0xffff0000, v193
	v_pk_fma_f32 v[30:31], v[80:81], v[86:87], v[30:31]
	v_pk_fma_f32 v[32:33], v[82:83], v[96:97], v[32:33]
	s_mov_b64 exec, -1
	v_cvt_pk_bf16_f32 v52, v26, v27
	v_cvt_pk_bf16_f32 v53, v28, v29
	v_cvt_pk_bf16_f32 v54, v30, v31
	v_cvt_pk_bf16_f32 v55, v32, v33
	s_waitcnt lgkmcnt(3)
	s_waitcnt lgkmcnt(1)
	s_waitcnt lgkmcnt(0)
	s_nop 0
	global_load_dwordx4 v[178:181], v[0:1], off offset:192
	global_load_dwordx4 v[182:185], v[4:5], off offset:192
	global_load_dwordx4 v[186:189], v[2:3], off offset:192
	global_load_dwordx4 v[190:193], v[6:7], off offset:192
	s_waitcnt vmcnt(7)
	s_waitcnt vmcnt(7)
	s_waitcnt lgkmcnt(3)
	s_waitcnt lgkmcnt(1)
	s_waitcnt lgkmcnt(0)
	s_waitcnt vmcnt(7)
	s_waitcnt vmcnt(7)
	ds_read_b128 v[26:29], v9 offset:10368
	ds_read_b128 v[30:33], v9 offset:10384
	ds_read_b128 v[34:37], v9 offset:8320
	ds_read_b128 v[38:41], v9 offset:8336
	ds_read_b128 v[42:45], v9 offset:8832
	ds_read_b128 v[80:83], v9 offset:8848
	s_mov_b64 exec, vcc
	v_lshlrev_b32_e32 v46, 16, v194
	v_and_b32_e32 v47, 0xffff0000, v194
	v_lshlrev_b32_e32 v84, 16, v195
	v_and_b32_e32 v85, 0xffff0000, v195
	s_waitcnt lgkmcnt(2)
	v_pk_fma_f32 v[26:27], v[34:35], v[46:47], v[26:27]
	v_pk_fma_f32 v[28:29], v[36:37], v[84:85], v[28:29]
	v_lshlrev_b32_e32 v86, 16, v196
	v_and_b32_e32 v87, 0xffff0000, v196
	v_lshlrev_b32_e32 v96, 16, v197
	v_and_b32_e32 v97, 0xffff0000, v197
	v_pk_fma_f32 v[30:31], v[38:39], v[86:87], v[30:31]
	v_pk_fma_f32 v[32:33], v[40:41], v[96:97], v[32:33]
	s_mov_b64 exec, -1
	ds_read_b128 v[34:37], v9 offset:9344
	ds_read_b128 v[38:41], v9 offset:9360
	s_mov_b64 exec, s[4:5]
	v_lshlrev_b32_e32 v46, 16, v198
	v_and_b32_e32 v47, 0xffff0000, v198
	v_lshlrev_b32_e32 v84, 16, v199
	v_and_b32_e32 v85, 0xffff0000, v199
	s_waitcnt lgkmcnt(2)
	v_pk_fma_f32 v[26:27], v[42:43], v[46:47], v[26:27]
	v_pk_fma_f32 v[28:29], v[44:45], v[84:85], v[28:29]
	v_lshlrev_b32_e32 v86, 16, v200
	v_and_b32_e32 v87, 0xffff0000, v200
	v_lshlrev_b32_e32 v96, 16, v201
	v_and_b32_e32 v97, 0xffff0000, v201
	v_pk_fma_f32 v[30:31], v[80:81], v[86:87], v[30:31]
	v_pk_fma_f32 v[32:33], v[82:83], v[96:97], v[32:33]
	s_mov_b64 exec, -1
	ds_read_b128 v[42:45], v9 offset:9856
	ds_read_b128 v[80:83], v9 offset:9872
	v_lshlrev_b32_e32 v46, 16, v202
	v_and_b32_e32 v47, 0xffff0000, v202
	v_lshlrev_b32_e32 v84, 16, v203
	v_and_b32_e32 v85, 0xffff0000, v203
	s_waitcnt lgkmcnt(2)
	v_pk_fma_f32 v[26:27], v[34:35], v[46:47], v[26:27]
	v_pk_fma_f32 v[28:29], v[36:37], v[84:85], v[28:29]
	v_lshlrev_b32_e32 v86, 16, v204
	v_and_b32_e32 v87, 0xffff0000, v204
	v_lshlrev_b32_e32 v96, 16, v205
	v_and_b32_e32 v97, 0xffff0000, v205
	v_pk_fma_f32 v[30:31], v[38:39], v[86:87], v[30:31]
	v_pk_fma_f32 v[32:33], v[40:41], v[96:97], v[32:33]
	s_mov_b64 exec, s[6:7]
	v_lshlrev_b32_e32 v46, 16, v206
	v_and_b32_e32 v47, 0xffff0000, v206
	v_lshlrev_b32_e32 v84, 16, v207
	v_and_b32_e32 v85, 0xffff0000, v207
	s_waitcnt lgkmcnt(0)
	v_pk_fma_f32 v[26:27], v[42:43], v[46:47], v[26:27]
	v_pk_fma_f32 v[28:29], v[44:45], v[84:85], v[28:29]
	v_lshlrev_b32_e32 v86, 16, v208
	v_and_b32_e32 v87, 0xffff0000, v208
	v_lshlrev_b32_e32 v96, 16, v209
	v_and_b32_e32 v97, 0xffff0000, v209
	v_pk_fma_f32 v[30:31], v[80:81], v[86:87], v[30:31]
	v_pk_fma_f32 v[32:33], v[82:83], v[96:97], v[32:33]
	s_mov_b64 exec, -1
	v_cvt_pk_bf16_f32 v56, v26, v27
	v_cvt_pk_bf16_f32 v57, v28, v29
	v_cvt_pk_bf16_f32 v58, v30, v31
	v_cvt_pk_bf16_f32 v59, v32, v33
	s_waitcnt lgkmcnt(3)
	s_waitcnt lgkmcnt(1)
	s_waitcnt lgkmcnt(0)
	s_nop 0
	global_load_dwordx4 v[194:197], v[0:1], off offset:224
	global_load_dwordx4 v[198:201], v[4:5], off offset:224
	global_load_dwordx4 v[202:205], v[2:3], off offset:224
	global_load_dwordx4 v[206:209], v[6:7], off offset:224
	s_waitcnt vmcnt(10)
	s_waitcnt vmcnt(10)
	s_waitcnt lgkmcnt(3)
	s_waitcnt lgkmcnt(1)
	s_waitcnt lgkmcnt(0)
	s_waitcnt vmcnt(10)
	s_waitcnt vmcnt(10)
	ds_read_b128 v[0:3], v9 offset:10432
	ds_read_b128 v[4:7], v9 offset:10448
	ds_read_b128 v[26:29], v9 offset:8384
	ds_read_b128 v[30:33], v9 offset:8400
	ds_read_b128 v[34:37], v9 offset:8896
	ds_read_b128 v[38:41], v9 offset:8912
	s_mov_b64 exec, vcc
	v_lshlrev_b32_e32 v42, 16, v210
	v_and_b32_e32 v43, 0xffff0000, v210
	v_lshlrev_b32_e32 v44, 16, v211
	v_and_b32_e32 v45, 0xffff0000, v211
	s_waitcnt lgkmcnt(2)
	v_pk_fma_f32 v[0:1], v[26:27], v[42:43], v[0:1]
	v_pk_fma_f32 v[2:3], v[28:29], v[44:45], v[2:3]
	v_lshlrev_b32_e32 v46, 16, v212
	v_and_b32_e32 v47, 0xffff0000, v212
	v_lshlrev_b32_e32 v80, 16, v213
	v_and_b32_e32 v81, 0xffff0000, v213
	v_pk_fma_f32 v[4:5], v[30:31], v[46:47], v[4:5]
	v_pk_fma_f32 v[6:7], v[32:33], v[80:81], v[6:7]
	s_mov_b64 exec, -1
	ds_read_b128 v[26:29], v9 offset:9408
	ds_read_b128 v[30:33], v9 offset:9424
	s_mov_b64 exec, s[4:5]
	v_lshlrev_b32_e32 v42, 16, v214
	v_and_b32_e32 v43, 0xffff0000, v214
	v_lshlrev_b32_e32 v44, 16, v215
	v_and_b32_e32 v45, 0xffff0000, v215
	s_waitcnt lgkmcnt(2)
	v_pk_fma_f32 v[0:1], v[34:35], v[42:43], v[0:1]
	v_pk_fma_f32 v[2:3], v[36:37], v[44:45], v[2:3]
	v_lshlrev_b32_e32 v46, 16, v216
	v_and_b32_e32 v47, 0xffff0000, v216
	v_lshlrev_b32_e32 v80, 16, v217
	v_and_b32_e32 v81, 0xffff0000, v217
	v_pk_fma_f32 v[4:5], v[38:39], v[46:47], v[4:5]
	v_pk_fma_f32 v[6:7], v[40:41], v[80:81], v[6:7]
	s_mov_b64 exec, -1
	ds_read_b128 v[34:37], v9 offset:9920
	ds_read_b128 v[38:41], v9 offset:9936
	v_lshlrev_b32_e32 v42, 16, v218
	v_and_b32_e32 v43, 0xffff0000, v218
	v_lshlrev_b32_e32 v44, 16, v219
	v_and_b32_e32 v45, 0xffff0000, v219
	s_waitcnt lgkmcnt(2)
	v_pk_fma_f32 v[0:1], v[26:27], v[42:43], v[0:1]
	v_pk_fma_f32 v[2:3], v[28:29], v[44:45], v[2:3]
	v_lshlrev_b32_e32 v46, 16, v220
	v_and_b32_e32 v47, 0xffff0000, v220
	v_lshlrev_b32_e32 v80, 16, v221
	v_and_b32_e32 v81, 0xffff0000, v221
	v_pk_fma_f32 v[4:5], v[30:31], v[46:47], v[4:5]
	v_pk_fma_f32 v[6:7], v[32:33], v[80:81], v[6:7]
	s_mov_b64 exec, s[6:7]
	v_lshlrev_b32_e32 v42, 16, v222
	v_and_b32_e32 v43, 0xffff0000, v222
	v_lshlrev_b32_e32 v44, 16, v223
	v_and_b32_e32 v45, 0xffff0000, v223
	s_waitcnt lgkmcnt(0)
	v_pk_fma_f32 v[0:1], v[34:35], v[42:43], v[0:1]
	v_pk_fma_f32 v[2:3], v[36:37], v[44:45], v[2:3]
	v_lshlrev_b32_e32 v46, 16, v224
	v_and_b32_e32 v47, 0xffff0000, v224
	v_lshlrev_b32_e32 v80, 16, v225
	v_and_b32_e32 v81, 0xffff0000, v225
	v_pk_fma_f32 v[4:5], v[38:39], v[46:47], v[4:5]
	v_pk_fma_f32 v[6:7], v[40:41], v[80:81], v[6:7]
	s_mov_b64 exec, -1
	v_cvt_pk_bf16_f32 v60, v0, v1
	v_cvt_pk_bf16_f32 v61, v2, v3
	v_cvt_pk_bf16_f32 v62, v4, v5
	v_cvt_pk_bf16_f32 v63, v6, v7
	s_waitcnt lgkmcnt(3)
	s_waitcnt lgkmcnt(1)
	s_waitcnt lgkmcnt(0)
	s_nop 0
	s_waitcnt vmcnt(9)
	s_waitcnt vmcnt(9)
	s_waitcnt lgkmcnt(3)
	s_waitcnt lgkmcnt(1)
	s_waitcnt lgkmcnt(0)
	s_waitcnt vmcnt(9)
	s_waitcnt vmcnt(9)
	ds_read_b128 v[0:3], v9 offset:10496
	ds_read_b128 v[4:7], v9 offset:10512
	ds_read_b128 v[26:29], v9 offset:8448
	ds_read_b128 v[30:33], v9 offset:8464
	ds_read_b128 v[34:37], v9 offset:8960
	ds_read_b128 v[38:41], v9 offset:8976
	s_mov_b64 exec, vcc
	v_lshlrev_b32_e32 v42, 16, v226
	v_and_b32_e32 v43, 0xffff0000, v226
	v_lshlrev_b32_e32 v44, 16, v227
	v_and_b32_e32 v45, 0xffff0000, v227
	s_waitcnt lgkmcnt(2)
	v_pk_fma_f32 v[0:1], v[26:27], v[42:43], v[0:1]
	v_pk_fma_f32 v[2:3], v[28:29], v[44:45], v[2:3]
	v_lshlrev_b32_e32 v46, 16, v228
	v_and_b32_e32 v47, 0xffff0000, v228
	v_lshlrev_b32_e32 v80, 16, v229
	v_and_b32_e32 v81, 0xffff0000, v229
	v_pk_fma_f32 v[4:5], v[30:31], v[46:47], v[4:5]
	v_pk_fma_f32 v[6:7], v[32:33], v[80:81], v[6:7]
	s_mov_b64 exec, -1
	ds_read_b128 v[26:29], v9 offset:9472
	ds_read_b128 v[30:33], v9 offset:9488
	s_mov_b64 exec, s[4:5]
	v_lshlrev_b32_e32 v42, 16, v230
	v_and_b32_e32 v43, 0xffff0000, v230
	v_lshlrev_b32_e32 v44, 16, v231
	v_and_b32_e32 v45, 0xffff0000, v231
	s_waitcnt lgkmcnt(2)
	v_pk_fma_f32 v[0:1], v[34:35], v[42:43], v[0:1]
	v_pk_fma_f32 v[2:3], v[36:37], v[44:45], v[2:3]
	v_lshlrev_b32_e32 v46, 16, v232
	v_and_b32_e32 v47, 0xffff0000, v232
	v_lshlrev_b32_e32 v80, 16, v233
	v_and_b32_e32 v81, 0xffff0000, v233
	v_pk_fma_f32 v[4:5], v[38:39], v[46:47], v[4:5]
	v_pk_fma_f32 v[6:7], v[40:41], v[80:81], v[6:7]
	s_mov_b64 exec, -1
	ds_read_b128 v[34:37], v9 offset:9984
	ds_read_b128 v[38:41], v9 offset:10000
	v_lshlrev_b32_e32 v42, 16, v234
	v_and_b32_e32 v43, 0xffff0000, v234
	v_lshlrev_b32_e32 v44, 16, v235
	v_and_b32_e32 v45, 0xffff0000, v235
	s_waitcnt lgkmcnt(2)
	v_pk_fma_f32 v[0:1], v[26:27], v[42:43], v[0:1]
	v_pk_fma_f32 v[2:3], v[28:29], v[44:45], v[2:3]
	v_lshlrev_b32_e32 v46, 16, v236
	v_and_b32_e32 v47, 0xffff0000, v236
	v_lshlrev_b32_e32 v80, 16, v237
	v_and_b32_e32 v81, 0xffff0000, v237
	v_pk_fma_f32 v[4:5], v[30:31], v[46:47], v[4:5]
	v_pk_fma_f32 v[6:7], v[32:33], v[80:81], v[6:7]
	s_mov_b64 exec, s[6:7]
	v_lshlrev_b32_e32 v42, 16, v238
	v_and_b32_e32 v43, 0xffff0000, v238
	v_lshlrev_b32_e32 v44, 16, v239
	v_and_b32_e32 v45, 0xffff0000, v239
	s_waitcnt lgkmcnt(0)
	v_pk_fma_f32 v[0:1], v[34:35], v[42:43], v[0:1]
	v_pk_fma_f32 v[2:3], v[36:37], v[44:45], v[2:3]
	v_lshlrev_b32_e32 v46, 16, v240
	v_and_b32_e32 v47, 0xffff0000, v240
	v_lshlrev_b32_e32 v80, 16, v241
	v_and_b32_e32 v81, 0xffff0000, v241
	v_pk_fma_f32 v[4:5], v[38:39], v[46:47], v[4:5]
	v_pk_fma_f32 v[6:7], v[40:41], v[80:81], v[6:7]
	s_mov_b64 exec, -1
	v_cvt_pk_bf16_f32 v64, v0, v1
	v_cvt_pk_bf16_f32 v65, v2, v3
	v_cvt_pk_bf16_f32 v66, v4, v5
	v_cvt_pk_bf16_f32 v67, v6, v7
	s_waitcnt lgkmcnt(3)
	s_waitcnt lgkmcnt(1)
	s_waitcnt lgkmcnt(0)
	s_nop 0
	s_waitcnt vmcnt(8)
	s_waitcnt vmcnt(8)
	s_waitcnt lgkmcnt(3)
	s_waitcnt lgkmcnt(1)
	s_waitcnt lgkmcnt(0)
	s_waitcnt vmcnt(8)
	s_waitcnt vmcnt(8)
	ds_read_b128 v[0:3], v9 offset:10560
	ds_read_b128 v[4:7], v9 offset:10576
	ds_read_b128 v[26:29], v9 offset:8512
	ds_read_b128 v[30:33], v9 offset:8528
	ds_read_b128 v[34:37], v9 offset:9024
	ds_read_b128 v[38:41], v9 offset:9040
	s_mov_b64 exec, vcc
	v_lshlrev_b32_e32 v42, 16, v242
	v_and_b32_e32 v43, 0xffff0000, v242
	v_lshlrev_b32_e32 v44, 16, v243
	v_and_b32_e32 v45, 0xffff0000, v243
	s_waitcnt lgkmcnt(2)
	v_pk_fma_f32 v[0:1], v[26:27], v[42:43], v[0:1]
	v_pk_fma_f32 v[2:3], v[28:29], v[44:45], v[2:3]
	v_lshlrev_b32_e32 v46, 16, v244
	v_and_b32_e32 v47, 0xffff0000, v244
	v_lshlrev_b32_e32 v80, 16, v245
	v_and_b32_e32 v81, 0xffff0000, v245
	v_pk_fma_f32 v[4:5], v[30:31], v[46:47], v[4:5]
	v_pk_fma_f32 v[6:7], v[32:33], v[80:81], v[6:7]
	s_mov_b64 exec, -1
	ds_read_b128 v[26:29], v9 offset:9536
	ds_read_b128 v[30:33], v9 offset:9552
	s_mov_b64 exec, s[4:5]
	v_lshlrev_b32_e32 v42, 16, v246
	v_and_b32_e32 v43, 0xffff0000, v246
	v_lshlrev_b32_e32 v44, 16, v247
	v_and_b32_e32 v45, 0xffff0000, v247
	s_waitcnt lgkmcnt(2)
	v_pk_fma_f32 v[0:1], v[34:35], v[42:43], v[0:1]
	v_pk_fma_f32 v[2:3], v[36:37], v[44:45], v[2:3]
	v_lshlrev_b32_e32 v46, 16, v248
	v_and_b32_e32 v47, 0xffff0000, v248
	v_lshlrev_b32_e32 v80, 16, v249
	v_and_b32_e32 v81, 0xffff0000, v249
	v_pk_fma_f32 v[4:5], v[38:39], v[46:47], v[4:5]
	v_pk_fma_f32 v[6:7], v[40:41], v[80:81], v[6:7]
	s_mov_b64 exec, -1
	ds_read_b128 v[34:37], v9 offset:10048
	ds_read_b128 v[38:41], v9 offset:10064
	v_lshlrev_b32_e32 v42, 16, v252
	v_and_b32_e32 v43, 0xffff0000, v252
	v_lshlrev_b32_e32 v44, 16, v253
	v_and_b32_e32 v45, 0xffff0000, v253
	s_waitcnt lgkmcnt(2)
	v_pk_fma_f32 v[0:1], v[26:27], v[42:43], v[0:1]
	v_pk_fma_f32 v[2:3], v[28:29], v[44:45], v[2:3]
	v_lshlrev_b32_e32 v46, 16, v254
	v_and_b32_e32 v47, 0xffff0000, v254
	v_lshlrev_b32_e32 v80, 16, v255
	v_and_b32_e32 v81, 0xffff0000, v255
	v_pk_fma_f32 v[4:5], v[30:31], v[46:47], v[4:5]
	v_pk_fma_f32 v[6:7], v[32:33], v[80:81], v[6:7]
	s_mov_b64 exec, s[6:7]
	v_lshlrev_b32_e32 v42, 16, v168
	v_and_b32_e32 v43, 0xffff0000, v168
	v_lshlrev_b32_e32 v44, 16, v169
	v_and_b32_e32 v45, 0xffff0000, v169
	s_waitcnt lgkmcnt(0)
	v_pk_fma_f32 v[0:1], v[34:35], v[42:43], v[0:1]
	v_pk_fma_f32 v[2:3], v[36:37], v[44:45], v[2:3]
	v_lshlrev_b32_e32 v46, 16, v170
	v_and_b32_e32 v47, 0xffff0000, v170
	v_lshlrev_b32_e32 v80, 16, v171
	v_and_b32_e32 v81, 0xffff0000, v171
	v_pk_fma_f32 v[4:5], v[38:39], v[46:47], v[4:5]
	v_pk_fma_f32 v[6:7], v[40:41], v[80:81], v[6:7]
	s_mov_b64 exec, -1
	v_cvt_pk_bf16_f32 v68, v0, v1
	v_cvt_pk_bf16_f32 v69, v2, v3
	v_cvt_pk_bf16_f32 v70, v4, v5
	v_cvt_pk_bf16_f32 v71, v6, v7
	s_waitcnt lgkmcnt(3)
	s_waitcnt lgkmcnt(1)
	s_waitcnt lgkmcnt(0)
	s_nop 0
	s_waitcnt vmcnt(4)
	s_waitcnt vmcnt(4)
	s_waitcnt lgkmcnt(3)
	s_waitcnt lgkmcnt(1)
	s_waitcnt lgkmcnt(0)
	s_waitcnt vmcnt(4)
	s_waitcnt vmcnt(4)
	ds_read_b128 v[0:3], v9 offset:10624
	ds_read_b128 v[4:7], v9 offset:10640
	ds_read_b128 v[26:29], v9 offset:8576
	ds_read_b128 v[30:33], v9 offset:8592
	ds_read_b128 v[34:37], v9 offset:9088
	ds_read_b128 v[38:41], v9 offset:9104
	s_mov_b64 exec, vcc
	v_lshlrev_b32_e32 v42, 16, v178
	v_and_b32_e32 v43, 0xffff0000, v178
	v_lshlrev_b32_e32 v44, 16, v179
	v_and_b32_e32 v45, 0xffff0000, v179
	s_waitcnt lgkmcnt(2)
	v_pk_fma_f32 v[0:1], v[26:27], v[42:43], v[0:1]
	v_pk_fma_f32 v[2:3], v[28:29], v[44:45], v[2:3]
	v_lshlrev_b32_e32 v46, 16, v180
	v_and_b32_e32 v47, 0xffff0000, v180
	v_lshlrev_b32_e32 v80, 16, v181
	v_and_b32_e32 v81, 0xffff0000, v181
	v_pk_fma_f32 v[4:5], v[30:31], v[46:47], v[4:5]
	v_pk_fma_f32 v[6:7], v[32:33], v[80:81], v[6:7]
	s_mov_b64 exec, -1
	ds_read_b128 v[26:29], v9 offset:9600
	ds_read_b128 v[30:33], v9 offset:9616
	s_mov_b64 exec, s[4:5]
	v_lshlrev_b32_e32 v42, 16, v182
	v_and_b32_e32 v43, 0xffff0000, v182
	v_lshlrev_b32_e32 v44, 16, v183
	v_and_b32_e32 v45, 0xffff0000, v183
	s_waitcnt lgkmcnt(2)
	v_pk_fma_f32 v[0:1], v[34:35], v[42:43], v[0:1]
	v_pk_fma_f32 v[2:3], v[36:37], v[44:45], v[2:3]
	v_lshlrev_b32_e32 v46, 16, v184
	v_and_b32_e32 v47, 0xffff0000, v184
	v_lshlrev_b32_e32 v80, 16, v185
	v_and_b32_e32 v81, 0xffff0000, v185
	v_pk_fma_f32 v[4:5], v[38:39], v[46:47], v[4:5]
	v_pk_fma_f32 v[6:7], v[40:41], v[80:81], v[6:7]
	s_mov_b64 exec, -1
	ds_read_b128 v[34:37], v9 offset:10112
	ds_read_b128 v[38:41], v9 offset:10128
	v_lshlrev_b32_e32 v42, 16, v186
	v_and_b32_e32 v43, 0xffff0000, v186
	v_lshlrev_b32_e32 v44, 16, v187
	v_and_b32_e32 v45, 0xffff0000, v187
	s_waitcnt lgkmcnt(2)
	v_pk_fma_f32 v[0:1], v[26:27], v[42:43], v[0:1]
	v_pk_fma_f32 v[2:3], v[28:29], v[44:45], v[2:3]
	v_lshlrev_b32_e32 v46, 16, v188
	v_and_b32_e32 v47, 0xffff0000, v188
	v_lshlrev_b32_e32 v80, 16, v189
	v_and_b32_e32 v81, 0xffff0000, v189
	v_pk_fma_f32 v[4:5], v[30:31], v[46:47], v[4:5]
	v_pk_fma_f32 v[6:7], v[32:33], v[80:81], v[6:7]
	s_mov_b64 exec, s[6:7]
	v_lshlrev_b32_e32 v42, 16, v190
	v_and_b32_e32 v43, 0xffff0000, v190
	v_lshlrev_b32_e32 v44, 16, v191
	v_and_b32_e32 v45, 0xffff0000, v191
	s_waitcnt lgkmcnt(0)
	v_pk_fma_f32 v[0:1], v[34:35], v[42:43], v[0:1]
	v_pk_fma_f32 v[2:3], v[36:37], v[44:45], v[2:3]
	v_lshlrev_b32_e32 v46, 16, v192
	v_and_b32_e32 v47, 0xffff0000, v192
	v_lshlrev_b32_e32 v80, 16, v193
	v_and_b32_e32 v81, 0xffff0000, v193
	v_pk_fma_f32 v[4:5], v[38:39], v[46:47], v[4:5]
	v_pk_fma_f32 v[6:7], v[40:41], v[80:81], v[6:7]
	s_mov_b64 exec, -1
	v_cvt_pk_bf16_f32 v72, v0, v1
	v_cvt_pk_bf16_f32 v73, v2, v3
	v_cvt_pk_bf16_f32 v74, v4, v5
	v_cvt_pk_bf16_f32 v75, v6, v7
	s_waitcnt lgkmcnt(3)
	s_waitcnt lgkmcnt(1)
	s_waitcnt lgkmcnt(0)
	v_lshlrev_b32_e32 v38, 3, v92
	s_nop 0
	s_nop 0
	v_or_b32_e32 v39, 16, v38
	s_waitcnt vmcnt(0)
	s_waitcnt vmcnt(0)
	s_waitcnt lgkmcnt(3)
	s_waitcnt lgkmcnt(1)
	s_waitcnt lgkmcnt(0)
	s_waitcnt vmcnt(0)
	s_waitcnt vmcnt(0)
	ds_read_b128 v[0:3], v9 offset:10688
	ds_read_b128 v[4:7], v9 offset:10704
	ds_read_b128 v[26:29], v9 offset:8640
	ds_read_b128 v[30:33], v9 offset:8656
	ds_read_b128 v[34:37], v9 offset:9152
	ds_read_b128 v[40:43], v9 offset:9168
	s_mov_b64 exec, vcc
	v_lshlrev_b32_e32 v44, 16, v194
	v_and_b32_e32 v45, 0xffff0000, v194
	v_lshlrev_b32_e32 v46, 16, v195
	v_and_b32_e32 v47, 0xffff0000, v195
	s_waitcnt lgkmcnt(2)
	v_pk_fma_f32 v[0:1], v[26:27], v[44:45], v[0:1]
	v_pk_fma_f32 v[2:3], v[28:29], v[46:47], v[2:3]
	v_lshlrev_b32_e32 v80, 16, v196
	v_and_b32_e32 v81, 0xffff0000, v196
	v_lshlrev_b32_e32 v82, 16, v197
	v_and_b32_e32 v83, 0xffff0000, v197
	v_pk_fma_f32 v[4:5], v[30:31], v[80:81], v[4:5]
	v_pk_fma_f32 v[6:7], v[32:33], v[82:83], v[6:7]
	s_mov_b64 exec, -1
	ds_read_b128 v[26:29], v9 offset:9664
	ds_read_b128 v[30:33], v9 offset:9680
	s_mov_b64 exec, s[4:5]
	v_lshlrev_b32_e32 v44, 16, v198
	v_and_b32_e32 v45, 0xffff0000, v198
	v_lshlrev_b32_e32 v46, 16, v199
	v_and_b32_e32 v47, 0xffff0000, v199
	s_waitcnt lgkmcnt(2)
	v_pk_fma_f32 v[0:1], v[34:35], v[44:45], v[0:1]
	v_pk_fma_f32 v[2:3], v[36:37], v[46:47], v[2:3]
	v_lshlrev_b32_e32 v80, 16, v200
	v_and_b32_e32 v81, 0xffff0000, v200
	v_lshlrev_b32_e32 v82, 16, v201
	v_and_b32_e32 v83, 0xffff0000, v201
	v_pk_fma_f32 v[4:5], v[40:41], v[80:81], v[4:5]
	v_pk_fma_f32 v[6:7], v[42:43], v[82:83], v[6:7]
	s_mov_b64 exec, -1
	ds_read_b128 v[34:37], v9 offset:10176
	ds_read_b128 v[40:43], v9 offset:10192
	v_lshlrev_b32_e32 v44, 16, v202
	v_and_b32_e32 v45, 0xffff0000, v202
	v_lshlrev_b32_e32 v46, 16, v203
	v_and_b32_e32 v47, 0xffff0000, v203
	s_waitcnt lgkmcnt(2)
	v_pk_fma_f32 v[0:1], v[26:27], v[44:45], v[0:1]
	v_pk_fma_f32 v[2:3], v[28:29], v[46:47], v[2:3]
	v_lshlrev_b32_e32 v80, 16, v204
	v_and_b32_e32 v81, 0xffff0000, v204
	v_lshlrev_b32_e32 v82, 16, v205
	v_and_b32_e32 v83, 0xffff0000, v205
	v_pk_fma_f32 v[4:5], v[30:31], v[80:81], v[4:5]
	v_pk_fma_f32 v[6:7], v[32:33], v[82:83], v[6:7]
	s_mov_b64 exec, s[6:7]
	v_lshlrev_b32_e32 v44, 16, v206
	v_and_b32_e32 v45, 0xffff0000, v206
	v_lshlrev_b32_e32 v46, 16, v207
	v_and_b32_e32 v47, 0xffff0000, v207
	s_waitcnt lgkmcnt(0)
	v_pk_fma_f32 v[0:1], v[34:35], v[44:45], v[0:1]
	v_pk_fma_f32 v[2:3], v[36:37], v[46:47], v[2:3]
	v_lshlrev_b32_e32 v80, 16, v208
	v_and_b32_e32 v81, 0xffff0000, v208
	v_lshlrev_b32_e32 v82, 16, v209
	v_and_b32_e32 v83, 0xffff0000, v209
	v_pk_fma_f32 v[4:5], v[40:41], v[80:81], v[4:5]
	v_pk_fma_f32 v[6:7], v[42:43], v[82:83], v[6:7]
	s_mov_b64 exec, -1
	v_cvt_pk_bf16_f32 v76, v0, v1
	v_cvt_pk_bf16_f32 v77, v2, v3
	v_cvt_pk_bf16_f32 v78, v4, v5
	v_cvt_pk_bf16_f32 v79, v6, v7
	s_waitcnt lgkmcnt(3)
	s_waitcnt lgkmcnt(1)
	s_waitcnt lgkmcnt(0)
	v_cmp_eq_u32_e32 vcc, v38, v93
	v_or_b32_e32 v2, 1, v38
	v_cndmask_b32_e32 v0, 0, v128, vcc
	v_or_b32_e32 v1, 2, v38
	v_cmp_eq_u32_e32 vcc, v2, v93
	v_or_b32_e32 v4, 3, v38
	v_or_b32_e32 v3, 4, v38
	v_cndmask_b32_e32 v2, 0, v128, vcc
	v_cmp_eq_u32_e32 vcc, v1, v93
	v_or_b32_e32 v5, 6, v38
	v_or_b32_e32 v6, 5, v38
	v_cndmask_b32_e32 v1, 0, v128, vcc
	v_cmp_eq_u32_e32 vcc, v4, v93
	v_or_b32_e32 v7, 7, v38
	v_or_b32_e32 v11, 17, v38
	v_cndmask_b32_e32 v4, 0, v128, vcc
	v_cmp_eq_u32_e32 vcc, v3, v93
	v_or_b32_e32 v10, 18, v38
	v_or_b32_e32 v13, 19, v38
	v_cndmask_b32_e32 v3, 0, v128, vcc
	v_cmp_eq_u32_e32 vcc, v5, v93
	v_or_b32_e32 v12, 20, v38
	v_or_b32_e32 v14, 22, v38
	v_cndmask_b32_e32 v5, 0, v128, vcc
	v_cmp_eq_u32_e32 vcc, v6, v93
	v_or_b32_e32 v15, 21, v38
	v_or_b32_e32 v16, 23, v38
	v_cndmask_b32_e32 v6, 0, v128, vcc
	v_cmp_eq_u32_e32 vcc, v7, v93
	v_and_b32_e32 v18, 64, v126
	v_xor_b32_e32 v17, 32, v126
	v_cndmask_b32_e32 v7, 0, v128, vcc
	v_cmp_eq_u32_e32 vcc, v39, v93
	v_add_u32_e32 v18, 64, v18
	s_lshl_b32 s6, s64, 8
	v_cndmask_b32_e32 v9, 0, v128, vcc
	v_cmp_eq_u32_e32 vcc, v11, v93
	s_add_i32 s6, s6, 16
	v_cmp_eq_u32_e64 s[4:5], 0, v92
	v_cndmask_b32_e32 v11, 0, v128, vcc
	v_cmp_eq_u32_e32 vcc, v10, v93
	v_lshl_add_u32 v136, v93, 3, s6
	v_perm_b32 v82, v6, v3, s87
	v_cndmask_b32_e32 v10, 0, v128, vcc
	v_cmp_eq_u32_e32 vcc, v13, v93
	v_perm_b32 v81, v4, v1, s87
	v_perm_b32 v83, v7, v5, s87
	v_cndmask_b32_e32 v13, 0, v128, vcc
	v_cmp_eq_u32_e32 vcc, v12, v93
	v_perm_b32 v80, v2, v0, s87
	v_perm_b32 v85, v13, v10, s87
	v_cndmask_b32_e32 v12, 0, v128, vcc
	v_cmp_eq_u32_e32 vcc, v14, v93
	v_perm_b32 v84, v11, v9, s87
	s_nop 0
	v_cndmask_b32_e32 v14, 0, v128, vcc
	v_cmp_eq_u32_e32 vcc, v15, v93
	s_nop 1
	v_cndmask_b32_e32 v15, 0, v128, vcc
	v_cmp_eq_u32_e32 vcc, v16, v93
	v_perm_b32 v86, v15, v12, s87
	s_nop 0
	v_cndmask_b32_e32 v16, 0, v128, vcc
	v_cmp_lt_i32_e32 vcc, v17, v18
	v_perm_b32 v87, v16, v14, s87
	s_nop 0
	v_cndmask_b32_e32 v17, v126, v17, vcc
	v_lshlrev_b32_e32 v137, 2, v17
	v_lshl_or_b32 v175, v138, 2, v129
	global_load_dword v172, v175, s[42:43]
	global_load_dword v173, v175, s[36:37]
	global_load_dword v174, v175, s[40:41]
	s_setprio 1
	v_xad_u32 v145, v88, v8, v94
	ds_read_b128 v[0:3], v145 offset:16384
	ds_read_b128 v[4:7], v145 offset:49152
	s_waitcnt lgkmcnt(1)
	v_mfma_f32_32x32x16_bf16 v[32:47], v[48:51], v[0:3], 0
	v_or_b32_e32 v0, 32, v88
	v_xad_u32 v147, v0, v8, v94
	s_waitcnt lgkmcnt(0)
	v_mfma_f32_32x32x16_bf16 v[16:31], v[48:51], v[4:7], 0
	ds_read_b128 v[0:3], v147 offset:16384
	ds_read_b128 v[4:7], v147 offset:49152
	s_waitcnt lgkmcnt(1)
	v_mfma_f32_32x32x16_bf16 v[32:47], v[52:55], v[0:3], v[32:47]
	v_or_b32_e32 v0, 64, v88
	v_xad_u32 v142, v0, v8, v94
	s_waitcnt lgkmcnt(0)
	v_mfma_f32_32x32x16_bf16 v[16:31], v[52:55], v[4:7], v[16:31]
	ds_read_b128 v[0:3], v142 offset:16384
	ds_read_b128 v[4:7], v142 offset:49152
	s_waitcnt lgkmcnt(1)
	v_mfma_f32_32x32x16_bf16 v[32:47], v[56:59], v[0:3], v[32:47]
	v_or_b32_e32 v0, 0x60, v88
	v_xad_u32 v146, v0, v8, v94
	s_waitcnt lgkmcnt(0)
	v_mfma_f32_32x32x16_bf16 v[16:31], v[56:59], v[4:7], v[16:31]
	ds_read_b128 v[0:3], v146 offset:16384
	ds_read_b128 v[4:7], v146 offset:49152
	s_waitcnt lgkmcnt(1)
	v_mfma_f32_32x32x16_bf16 v[32:47], v[60:63], v[0:3], v[32:47]
	v_or_b32_e32 v0, 0x80, v88
	v_xad_u32 v141, v0, v8, v94
	s_waitcnt lgkmcnt(0)
	v_mfma_f32_32x32x16_bf16 v[16:31], v[60:63], v[4:7], v[16:31]
	ds_read_b128 v[0:3], v141 offset:16384
	ds_read_b128 v[4:7], v141 offset:49152
	s_waitcnt lgkmcnt(1)
	v_mfma_f32_32x32x16_bf16 v[32:47], v[64:67], v[0:3], v[32:47]
	v_or_b32_e32 v0, 0xa0, v88
	v_xad_u32 v144, v0, v8, v94
	s_waitcnt lgkmcnt(0)
	v_mfma_f32_32x32x16_bf16 v[16:31], v[64:67], v[4:7], v[16:31]
	ds_read_b128 v[0:3], v144 offset:16384
	ds_read_b128 v[4:7], v144 offset:49152
	s_waitcnt lgkmcnt(1)
	v_mfma_f32_32x32x16_bf16 v[32:47], v[68:71], v[0:3], v[32:47]
	v_or_b32_e32 v0, 0xc0, v88
	v_xad_u32 v139, v0, v8, v94
	s_waitcnt lgkmcnt(0)
	v_mfma_f32_32x32x16_bf16 v[16:31], v[68:71], v[4:7], v[16:31]
	ds_read_b128 v[0:3], v139 offset:16384
	ds_read_b128 v[4:7], v139 offset:49152
	s_waitcnt lgkmcnt(1)
	v_mfma_f32_32x32x16_bf16 v[32:47], v[72:75], v[0:3], v[32:47]
	v_or_b32_e32 v0, 0xe0, v88
	v_xad_u32 v143, v0, v8, v94
	s_waitcnt lgkmcnt(0)
	v_mfma_f32_32x32x16_bf16 v[16:31], v[72:75], v[4:7], v[16:31]
	ds_read_b128 v[0:3], v143 offset:16384
	ds_read_b128 v[4:7], v143 offset:49152
	s_waitcnt lgkmcnt(1)
	v_mfma_f32_32x32x16_bf16 v[32:47], v[76:79], v[0:3], v[32:47]
	s_waitcnt lgkmcnt(0)
	v_mfma_f32_32x32x16_bf16 v[16:31], v[76:79], v[4:7], v[16:31]
	v_mfma_f32_32x32x16_bf16 v[0:15], v[48:51], v[80:83], 0
	v_mfma_f32_32x32x16_bf16 v[0:15], v[52:55], v[84:87], v[0:15]
	s_setprio 0
	v_lshl_or_b32 v88, v138, 2, v129
	s_waitcnt vmcnt(0)
	ds_read_b32 v251, v167
	v_mul_f32_e32 v94, 0xbfb8aa3b, v173
	v_mul_f32_e32 v88, 0xbfb8aa3b, v174
	v_fmamk_f32 v32, v32, 0xbfb8aa3b, v94
	v_fmamk_f32 v16, v16, 0xbfb8aa3b, v88
	v_exp_f32_e32 v32, v32
	v_exp_f32_e32 v96, v16
	v_fmamk_f32 v17, v17, 0xbfb8aa3b, v88
	v_exp_f32_e32 v97, v17
	v_add_f32_e32 v32, 1.0, v32
	v_add_f32_e32 v96, 1.0, v96
	v_rcp_f32_e32 v17, v32
	v_rcp_f32_e32 v32, v96
	v_fmamk_f32 v33, v33, 0xbfb8aa3b, v94
	v_fmamk_f32 v34, v34, 0xbfb8aa3b, v94
	v_exp_f32_e32 v33, v33
	v_exp_f32_e32 v34, v34
	v_add_f32_e32 v33, 1.0, v33
	v_add_f32_e32 v34, 1.0, v34
	v_rcp_f32_e32 v33, v33
	v_rcp_f32_e32 v34, v34
	v_fmamk_f32 v18, v18, 0xbfb8aa3b, v88
	v_fmamk_f32 v19, v19, 0xbfb8aa3b, v88
	v_exp_f32_e32 v18, v18
	s_waitcnt lgkmcnt(0)
	v_mul_f32_e32 v95, 0x3fb8aa3b, v251
	v_mul_f32_e32 v16, v17, v95
	v_mul_f32_e32 v17, v33, v95
	v_exp_f32_e32 v33, v16
	v_mul_f32_e32 v16, v34, v95
	v_exp_f32_e32 v98, v16
	v_fmamk_f32 v16, v35, 0xbfb8aa3b, v94
	v_exp_f32_e32 v16, v16
	v_exp_f32_e32 v96, v17
	v_add_f32_e32 v16, 1.0, v16
	v_rcp_f32_e32 v16, v16
	v_exp_f32_e32 v19, v19
	v_add_f32_e32 v97, 1.0, v97
	v_add_f32_e32 v18, 1.0, v18
	v_mul_f32_e32 v16, v16, v95
	v_exp_f32_e32 v16, v16
	v_fma_f32 v35, -v98, v98, 1.0
	v_rcp_f32_e32 v17, v97
	v_fma_f32 v34, -v33, v33, 1.0
	v_fma_f32 v97, -v96, v96, 1.0
	v_rcp_f32_e32 v18, v18
	v_sqrt_f32_e32 v35, v35
	v_add_f32_e32 v19, 1.0, v19
	v_fma_f32 v99, -v16, v16, 1.0
	v_sqrt_f32_e32 v34, v34
	v_sqrt_f32_e32 v97, v97
	v_rcp_f32_e32 v19, v19
	v_sqrt_f32_e32 v99, v99
	v_mul_f32_e32 v35, v18, v35
	v_fmamk_f32 v18, v36, 0xbfb8aa3b, v94
	v_mul_f32_e32 v32, v32, v34
	v_mul_f32_e32 v34, v17, v97
	v_mul_f32_e32 v17, v19, v99
	v_fmamk_f32 v19, v20, 0xbfb8aa3b, v88
	v_exp_f32_e32 v18, v18
	v_exp_f32_e32 v19, v19
	v_mul_f32_e32 v3, v3, v17
	v_add_f32_e32 v17, 1.0, v18
	v_rcp_f32_e32 v17, v17
	v_add_f32_e32 v18, 1.0, v19
	v_fmamk_f32 v19, v37, 0xbfb8aa3b, v94
	v_exp_f32_e32 v19, v19
	v_mul_f32_e32 v17, v17, v95
	v_exp_f32_e32 v36, v17
	v_add_f32_e32 v17, 1.0, v19
	v_rcp_f32_e32 v17, v17
	v_fmamk_f32 v19, v21, 0xbfb8aa3b, v88
	v_exp_f32_e32 v19, v19
	v_mul_f32_e32 v17, v17, v95
	v_exp_f32_e32 v37, v17
	v_fmamk_f32 v17, v38, 0xbfb8aa3b, v94
	v_exp_f32_e32 v17, v17
	v_fmamk_f32 v23, v23, 0xbfb8aa3b, v88
	v_add_f32_e32 v19, 1.0, v19
	v_fma_f32 v21, -v37, v37, 1.0
	v_add_f32_e32 v17, 1.0, v17
	v_rcp_f32_e32 v17, v17
	v_rcp_f32_e32 v19, v19
	v_sqrt_f32_e32 v21, v21
	v_mul_f32_e32 v17, v17, v95
	v_exp_f32_e32 v38, v17
	v_fmamk_f32 v17, v39, 0xbfb8aa3b, v94
	v_exp_f32_e32 v17, v17
	v_exp_f32_e32 v23, v23
	v_fma_f32 v20, -v36, v36, 1.0
	v_mul_f32_e32 v100, v19, v21
	v_add_f32_e32 v17, 1.0, v17
	v_rcp_f32_e32 v17, v17
	v_add_f32_e32 v23, 1.0, v23
	v_fmamk_f32 v19, v40, 0xbfb8aa3b, v94
	v_rcp_f32_e32 v18, v18
	v_mul_f32_e32 v17, v17, v95
	v_exp_f32_e32 v17, v17
	v_sqrt_f32_e32 v20, v20
	v_rcp_f32_e32 v23, v23
	v_fma_f32 v97, -v17, v17, 1.0
	v_sqrt_f32_e32 v97, v97
	v_fmamk_f32 v21, v24, 0xbfb8aa3b, v88
	v_fmamk_f32 v22, v22, 0xbfb8aa3b, v88
	v_exp_f32_e32 v19, v19
	v_exp_f32_e32 v21, v21
	v_exp_f32_e32 v22, v22
	v_mul_f32_e32 v99, v18, v20
	v_mul_f32_e32 v18, v23, v97
	v_mul_f32_e32 v7, v7, v18
	v_add_f32_e32 v18, 1.0, v19
	v_rcp_f32_e32 v18, v18
	v_add_f32_e32 v19, 1.0, v21
	v_fmamk_f32 v21, v41, 0xbfb8aa3b, v94
	v_add_f32_e32 v22, 1.0, v22
	v_fma_f32 v39, -v38, v38, 1.0
	v_rcp_f32_e32 v22, v22
	v_sqrt_f32_e32 v39, v39
	v_exp_f32_e32 v21, v21
	v_mul_f32_e32 v18, v18, v95
	v_mul_f32_e32 v20, v22, v39
	v_exp_f32_e32 v39, v18
	v_add_f32_e32 v18, 1.0, v21
	v_rcp_f32_e32 v18, v18
	v_fmamk_f32 v21, v25, 0xbfb8aa3b, v88
	v_exp_f32_e32 v21, v21
	v_mul_f32_e32 v18, v18, v95
	v_exp_f32_e32 v40, v18
	v_fmamk_f32 v18, v42, 0xbfb8aa3b, v94
	v_exp_f32_e32 v18, v18
	v_fmamk_f32 v24, v26, 0xbfb8aa3b, v88
	v_fmamk_f32 v26, v27, 0xbfb8aa3b, v88
	v_add_f32_e32 v21, 1.0, v21
	v_add_f32_e32 v18, 1.0, v18
	v_rcp_f32_e32 v18, v18
	v_fma_f32 v23, -v40, v40, 1.0
	v_fma_f32 v22, -v39, v39, 1.0
	v_mul_f32_e32 v18, v18, v95
	v_exp_f32_e32 v41, v18
	v_fmamk_f32 v18, v43, 0xbfb8aa3b, v94
	v_exp_f32_e32 v18, v18
	v_rcp_f32_e32 v21, v21
	v_sqrt_f32_e32 v23, v23
	v_exp_f32_e32 v26, v26
	v_add_f32_e32 v18, 1.0, v18
	v_rcp_f32_e32 v18, v18
	v_rcp_f32_e32 v19, v19
	v_sqrt_f32_e32 v22, v22
	v_add_f32_e32 v26, 1.0, v26
	v_mul_f32_e32 v18, v18, v95
	v_exp_f32_e32 v18, v18
	v_mul_f32_e32 v43, v21, v23
	v_fmamk_f32 v21, v44, 0xbfb8aa3b, v94
	v_rcp_f32_e32 v26, v26
	v_fma_f32 v27, -v18, v18, 1.0
	v_sqrt_f32_e32 v27, v27
	v_mul_f32_e32 v42, v19, v22
	v_fmamk_f32 v22, v28, 0xbfb8aa3b, v88
	v_exp_f32_e32 v21, v21
	v_exp_f32_e32 v22, v22
	v_mul_f32_e32 v19, v26, v27
	v_mul_f32_e32 v11, v11, v19
	v_add_f32_e32 v19, 1.0, v21
	v_rcp_f32_e32 v19, v19
	v_add_f32_e32 v21, 1.0, v22
	v_fmamk_f32 v22, v45, 0xbfb8aa3b, v94
	v_exp_f32_e32 v22, v22
	v_mul_f32_e32 v19, v19, v95
	v_exp_f32_e32 v44, v19
	v_add_f32_e32 v19, 1.0, v22
	v_rcp_f32_e32 v19, v19
	v_exp_f32_e32 v24, v24
	v_fma_f32 v25, -v41, v41, 1.0
	v_mul_f32_e32 v19, v19, v95
	v_exp_f32_e32 v45, v19
	v_fmamk_f32 v19, v46, 0xbfb8aa3b, v94
	v_exp_f32_e32 v19, v19
	v_add_f32_e32 v24, 1.0, v24
	v_rcp_f32_e32 v24, v24
	v_sqrt_f32_e32 v25, v25
	v_add_f32_e32 v19, 1.0, v19
	v_rcp_f32_e32 v19, v19
	v_fmamk_f32 v22, v29, 0xbfb8aa3b, v88
	v_mul_f32_e32 v97, v24, v25
	v_fma_f32 v24, -v45, v45, 1.0
	v_mul_f32_e32 v19, v19, v95
	v_exp_f32_e32 v46, v19
	v_fmamk_f32 v19, v47, 0xbfb8aa3b, v94
	v_exp_f32_e32 v19, v19
	v_sqrt_f32_e32 v25, v24
	v_fmamk_f32 v24, v30, 0xbfb8aa3b, v88
	v_exp_f32_e32 v24, v24
	v_add_f32_e32 v19, 1.0, v19
	v_rcp_f32_e32 v19, v19
	v_fma_f32 v27, -v46, v46, 1.0
	v_add_f32_e32 v24, 1.0, v24
	v_rcp_f32_e32 v26, v24
	v_fmamk_f32 v24, v31, 0xbfb8aa3b, v88
	v_mul_f32_e32 v19, v19, v95
	v_exp_f32_e32 v28, v24
	v_exp_f32_e32 v24, v19
	v_sqrt_f32_e32 v19, v27
	v_add_f32_e32 v27, 1.0, v28
	v_fma_f32 v28, -v24, v24, 1.0
	v_exp_f32_e32 v22, v22
	v_rcp_f32_e32 v27, v27
	v_sqrt_f32_e32 v28, v28
	v_fma_f32 v23, -v44, v44, 1.0
	v_rcp_f32_e32 v21, v21
	v_sqrt_f32_e32 v23, v23
	v_add_f32_e32 v22, 1.0, v22
	v_mul_f32_e32 v94, v26, v19
	v_mul_f32_e32 v19, v27, v28
	v_fmac_f32_e32 v7, 0, v17
	v_rcp_f32_e32 v22, v22
	v_mul_f32_e32 v15, v15, v19
	v_mul_f32_e32 v19, v38, v7
	v_fmac_f32_e32 v3, 0, v16
	v_fmac_f32_e32 v19, v6, v20
	v_mul_f32_e32 v47, v21, v23
	v_mul_f32_e32 v21, v98, v3
	v_mul_f32_e32 v20, v37, v19
	v_fmac_f32_e32 v15, 0, v24
	v_fmac_f32_e32 v21, v2, v35
	v_fmac_f32_e32 v20, v5, v100
	v_mul_f32_e32 v2, v46, v15
	v_mul_f32_e32 v88, v22, v25
	v_mul_f32_e32 v22, v36, v20
	v_fmac_f32_e32 v2, v14, v94
	v_fmac_f32_e32 v22, v4, v99
	v_mul_f32_e32 v4, v45, v2
	v_mul_f32_e32 v23, v96, v21
	v_fmac_f32_e32 v4, v13, v88
	v_fmac_f32_e32 v23, v1, v34
	v_fmac_f32_e32 v11, 0, v18
	v_mul_f32_e32 v14, v24, v46
	v_mul_f32_e32 v6, v44, v4
	v_mul_f32_e32 v25, v33, v23
	v_mul_f32_e32 v5, v41, v11
	v_mul_f32_e32 v13, v45, v14
	v_fmac_f32_e32 v6, v12, v47
	v_fmac_f32_e32 v25, v0, v32
	v_fmac_f32_e32 v5, v10, v97
	v_mul_f32_e32 v12, v44, v13
	ds_bpermute_b32 v0, v137, v6
	v_mul_f32_e32 v10, v40, v5
	ds_bpermute_b32 v35, v137, v12
	v_mul_f32_e32 v28, v18, v41
	v_fmac_f32_e32 v10, v9, v43
	v_mul_f32_e32 v26, v16, v98
	v_mul_f32_e32 v27, v17, v38
	v_mul_f32_e32 v31, v40, v28
	v_mul_f32_e32 v9, v39, v10
	v_mul_f32_e32 v29, v96, v26
	v_mul_f32_e32 v30, v37, v27
	v_fmac_f32_e32 v9, v8, v42
	v_mul_f32_e32 v34, v39, v31
	v_mul_f32_e32 v32, v33, v29
	v_mul_f32_e32 v33, v36, v30
	s_waitcnt lgkmcnt(1)
	v_cndmask_b32_e64 v36, v0, v6, s[4:5]
	v_cndmask_b32_e64 v37, v6, v0, s[4:5]
	ds_bpermute_b32 v0, v137, v34
	ds_bpermute_b32 v40, v137, v9
	s_waitcnt lgkmcnt(2)
	v_cndmask_b32_e64 v8, v12, v35, s[4:5]
	v_fmac_f32_e32 v37, 0, v8
	ds_bpermute_b32 v8, v137, v33
	v_cndmask_b32_e64 v1, v35, v12, s[4:5]
	v_mul_f32_e32 v38, v12, v35
	v_fmac_f32_e32 v36, v1, v37
	s_waitcnt lgkmcnt(2)
	v_cndmask_b32_e64 v1, v0, v34, s[4:5]
	s_waitcnt lgkmcnt(1)
	v_cndmask_b32_e64 v39, v40, v9, s[4:5]
	v_cndmask_b32_e64 v0, v34, v0, s[4:5]
	v_cndmask_b32_e64 v40, v9, v40, s[4:5]
	ds_bpermute_b32 v44, v137, v22
	v_mul_f32_e32 v41, v38, v0
	v_fmac_f32_e32 v40, v0, v36
	v_mul_f32_e32 v42, v1, v41
	v_fmac_f32_e32 v39, v1, v40
	s_waitcnt lgkmcnt(1)
	v_cndmask_b32_e64 v0, v8, v33, s[4:5]
	v_cndmask_b32_e64 v1, v33, v8, s[4:5]
	ds_bpermute_b32 v8, v137, v32
	ds_bpermute_b32 v47, v137, v25
	s_waitcnt lgkmcnt(2)
	v_cndmask_b32_e64 v43, v44, v22, s[4:5]
	v_cndmask_b32_e64 v44, v22, v44, s[4:5]
	v_mul_f32_e32 v45, v1, v42
	v_fmac_f32_e32 v44, v1, v39
	v_mul_f32_e32 v46, v0, v45
	v_fmac_f32_e32 v43, v0, v44
	s_waitcnt lgkmcnt(1)
	v_cndmask_b32_e64 v0, v32, v8, s[4:5]
	s_waitcnt lgkmcnt(0)
	v_cndmask_b32_e64 v47, v25, v47, s[4:5]
	v_mul_f32_e32 v88, v0, v46
	v_fmac_f32_e32 v47, v0, v43
	s_and_saveexec_b64 s[6:7], s[4:5]
	v_mul_f32_e32 v0, v32, v88
	v_fma_f32 v1, v32, v47, v25
	ds_write_b64 v136, v[0:1]
	s_or_b64 exec, exec, s[6:7]
	s_cmp_lt_i32 s64, 7
	s_cselect_b64 s[14:15], -1, 0
	s_cmp_gt_i32 s64, 6
	v_mul_i32_i24_e32 v140, 0xffffff08, v93
	s_waitcnt lgkmcnt(0)
	s_barrier
	s_cbranch_scc1 .LBB0_269
	v_add3_u32 v94, v140, v91, s92
	v_mov_b32_e32 v8, 1.0
	v_mov_b32_e32 v1, 0
	s_mov_b32 s6, 7

.LBB0_320:
	s_and_b32 s63, s57, 63
	s_ashr_i32 s62, s89, 6
	s_lshl_b32 s0, s63, 8
	s_lshl_b32 s1, s62, 5
	v_and_b32_e32 v94, 31, v92
	s_add_i32 s8, s1, s0
	v_or_b32_e32 v9, s8, v94
	v_add_u32_e32 v0, -2, v9
	v_cmp_gt_u32_e32 vcc, s80, v0
	v_bfe_u32 v93, v92, 5, 1
	s_lshl_b32 s14, s70, 1
	v_cndmask_b32_e32 v2, v9, v0, vcc
	v_mov_b64_e32 v[0:1], s[52:53]
	v_mad_i64_i32 v[2:3], s[0:1], v2, s81, v[0:1]
	v_lshl_add_u64 v[2:3], v[2:3], 0, s[14:15]
	v_lshlrev_b32_e32 v88, 4, v93
	v_lshl_add_u64 v[4:5], v[2:3], 0, v[88:89]
	v_add_co_u32_e64 v2, s[0:1], s82, v4
	s_waitcnt lgkmcnt(0)
	s_nop 0
	v_addc_co_u32_e64 v3, s[0:1], 0, v5, s[0:1]
	s_barrier
	global_load_dwordx4 v[10:13], v[2:3], off offset:1024
	global_load_dwordx4 v[178:181], v[2:3], off offset:1056
	global_load_dwordx4 v[194:197], v[2:3], off offset:1088
	global_load_dwordx4 v[210:213], v[2:3], off offset:1120
	global_load_dwordx4 v[226:229], v[2:3], off offset:1152
	global_load_dwordx4 v[242:245], v[2:3], off offset:1184
	v_add_u32_e32 v2, -1, v9
	v_cmp_gt_u32_e64 s[0:1], s80, v2
	v_add_u32_e32 v18, 1, v9
	s_cmpk_lt_u32 s8, 0x4000
	v_cndmask_b32_e64 v2, v9, v2, s[0:1]
	v_mad_i64_i32 v[2:3], s[4:5], v2, s81, v[0:1]
	v_lshl_add_u64 v[2:3], v[2:3], 0, s[14:15]
	v_lshl_add_u64 v[2:3], v[2:3], 0, v[88:89]
	v_add_co_u32_e64 v6, s[4:5], s82, v2
	v_lshlrev_b32_e32 v138, 8, v94
	s_nop 0
	v_addc_co_u32_e64 v7, s[4:5], 0, v3, s[4:5]
	global_load_dwordx4 v[14:17], v[6:7], off offset:1024
	global_load_dwordx4 v[182:185], v[6:7], off offset:1056
	global_load_dwordx4 v[198:201], v[6:7], off offset:1088
	global_load_dwordx4 v[214:217], v[6:7], off offset:1120
	global_load_dwordx4 v[230:233], v[6:7], off offset:1152
	global_load_dwordx4 v[246:249], v[6:7], off offset:1184
	v_mad_i64_i32 v[6:7], s[4:5], v9, s81, v[0:1]
	v_cmp_gt_u32_e64 s[4:5], s80, v18
	v_lshl_add_u64 v[6:7], v[6:7], 0, s[14:15]
	v_lshl_add_u64 v[52:53], v[6:7], 0, v[88:89]
	v_cndmask_b32_e64 v9, v9, v18, s[4:5]
	v_mad_i64_i32 v[0:1], s[6:7], v9, s81, v[0:1]
	v_add_co_u32_e64 v6, s[6:7], s82, v52
	v_lshl_add_u64 v[0:1], v[0:1], 0, s[14:15]
	s_nop 0
	v_addc_co_u32_e64 v7, s[6:7], 0, v53, s[6:7]
	global_load_dwordx4 v[18:21], v[6:7], off offset:1024
	global_load_dwordx4 v[186:189], v[6:7], off offset:1056
	global_load_dwordx4 v[202:205], v[6:7], off offset:1088
	global_load_dwordx4 v[218:221], v[6:7], off offset:1120
	global_load_dwordx4 v[234:237], v[6:7], off offset:1152
	global_load_dwordx4 v[252:255], v[6:7], off offset:1184
	v_lshl_add_u64 v[6:7], v[0:1], 0, v[88:89]
	v_add_co_u32_e64 v0, s[6:7], s82, v6
	v_lshl_add_u32 v9, v93, 5, 16
	s_nop 0
	v_addc_co_u32_e64 v1, s[6:7], 0, v7, s[6:7]
	global_load_dwordx4 v[22:25], v[0:1], off offset:1024
	global_load_dwordx4 v[190:193], v[0:1], off offset:1056
	global_load_dwordx4 v[206:209], v[0:1], off offset:1088
	global_load_dwordx4 v[222:225], v[0:1], off offset:1120
	global_load_dwordx4 v[238:241], v[0:1], off offset:1152
	global_load_dwordx4 v[168:171], v[0:1], off offset:1184
	s_waitcnt vmcnt(26)
	s_waitcnt lgkmcnt(4)
	v_lshl_add_u64 v[0:1], v[4:5], 0, s[30:31]
	s_cselect_b64 s[6:7], -1, 0
	v_lshl_add_u64 v[6:7], v[6:7], 0, s[30:31]
	v_and_b32_e32 v8, 0x70, v8
	v_add_u32_e32 v95, 16, v138
	v_or_b32_e32 v91, s70, v94
	s_waitcnt vmcnt(23)
	s_waitcnt vmcnt(17)
	s_waitcnt lgkmcnt(3)
	s_waitcnt lgkmcnt(1)
	s_waitcnt lgkmcnt(0)
	s_waitcnt vmcnt(11)
	s_waitcnt vmcnt(5)
	ds_read_b128 v[26:29], v9 offset:10240
	ds_read_b128 v[30:33], v9 offset:10256
	ds_read_b128 v[34:37], v9 offset:8192
	ds_read_b128 v[38:41], v9 offset:8208
	ds_read_b128 v[42:45], v9 offset:8704
	ds_read_b128 v[80:83], v9 offset:8720
	s_mov_b64 exec, vcc
	v_lshlrev_b32_e32 v4, 16, v10
	v_and_b32_e32 v5, 0xffff0000, v10
	v_lshlrev_b32_e32 v46, 16, v11
	v_and_b32_e32 v47, 0xffff0000, v11
	s_waitcnt lgkmcnt(2)
	v_pk_fma_f32 v[26:27], v[34:35], v[4:5], v[26:27]
	v_pk_fma_f32 v[28:29], v[36:37], v[46:47], v[28:29]
	v_lshlrev_b32_e32 v84, 16, v12
	v_and_b32_e32 v85, 0xffff0000, v12
	v_lshlrev_b32_e32 v86, 16, v13
	v_and_b32_e32 v87, 0xffff0000, v13
	v_pk_fma_f32 v[30:31], v[38:39], v[84:85], v[30:31]
	v_pk_fma_f32 v[32:33], v[40:41], v[86:87], v[32:33]
	s_mov_b64 exec, -1
	ds_read_b128 v[34:37], v9 offset:9216
	ds_read_b128 v[38:41], v9 offset:9232
	s_mov_b64 exec, s[0:1]
	v_lshlrev_b32_e32 v4, 16, v14
	v_and_b32_e32 v5, 0xffff0000, v14
	v_lshlrev_b32_e32 v46, 16, v15
	v_and_b32_e32 v47, 0xffff0000, v15
	s_waitcnt lgkmcnt(2)
	v_pk_fma_f32 v[26:27], v[42:43], v[4:5], v[26:27]
	v_pk_fma_f32 v[28:29], v[44:45], v[46:47], v[28:29]
	v_lshlrev_b32_e32 v84, 16, v16
	v_and_b32_e32 v85, 0xffff0000, v16
	v_lshlrev_b32_e32 v86, 16, v17
	v_and_b32_e32 v87, 0xffff0000, v17
	v_pk_fma_f32 v[30:31], v[80:81], v[84:85], v[30:31]
	v_pk_fma_f32 v[32:33], v[82:83], v[86:87], v[32:33]
	s_mov_b64 exec, -1
	ds_read_b128 v[42:45], v9 offset:9728
	ds_read_b128 v[80:83], v9 offset:9744
	v_lshlrev_b32_e32 v4, 16, v18
	v_and_b32_e32 v5, 0xffff0000, v18
	v_lshlrev_b32_e32 v46, 16, v19
	v_and_b32_e32 v47, 0xffff0000, v19
	s_waitcnt lgkmcnt(2)
	v_pk_fma_f32 v[26:27], v[34:35], v[4:5], v[26:27]
	v_pk_fma_f32 v[28:29], v[36:37], v[46:47], v[28:29]
	v_lshlrev_b32_e32 v84, 16, v20
	v_and_b32_e32 v85, 0xffff0000, v20
	v_lshlrev_b32_e32 v86, 16, v21
	v_and_b32_e32 v87, 0xffff0000, v21
	v_pk_fma_f32 v[30:31], v[38:39], v[84:85], v[30:31]
	v_pk_fma_f32 v[32:33], v[40:41], v[86:87], v[32:33]
	s_mov_b64 exec, s[4:5]
	v_lshlrev_b32_e32 v4, 16, v22
	v_and_b32_e32 v5, 0xffff0000, v22
	v_lshlrev_b32_e32 v46, 16, v23
	v_and_b32_e32 v47, 0xffff0000, v23
	s_waitcnt lgkmcnt(0)
	v_pk_fma_f32 v[26:27], v[42:43], v[4:5], v[26:27]
	v_pk_fma_f32 v[28:29], v[44:45], v[46:47], v[28:29]
	v_lshlrev_b32_e32 v84, 16, v24
	v_and_b32_e32 v85, 0xffff0000, v24
	v_lshlrev_b32_e32 v86, 16, v25
	v_and_b32_e32 v87, 0xffff0000, v25
	v_pk_fma_f32 v[30:31], v[80:81], v[84:85], v[30:31]
	v_pk_fma_f32 v[32:33], v[82:83], v[86:87], v[32:33]
	s_mov_b64 exec, -1
	v_cvt_pk_bf16_f32 v48, v26, v27
	v_cvt_pk_bf16_f32 v49, v28, v29
	v_cvt_pk_bf16_f32 v50, v30, v31
	v_cvt_pk_bf16_f32 v51, v32, v33
	s_waitcnt lgkmcnt(3)
	s_waitcnt lgkmcnt(1)
	s_waitcnt lgkmcnt(0)
	s_nop 0
	v_lshl_add_u64 v[4:5], v[2:3], 0, s[30:31]
	v_lshl_add_u64 v[2:3], v[52:53], 0, s[30:31]
	s_waitcnt vmcnt(4)
	s_waitcnt vmcnt(4)
	s_waitcnt lgkmcnt(3)
	s_waitcnt lgkmcnt(1)
	s_waitcnt lgkmcnt(0)
	s_waitcnt vmcnt(4)
	ds_read_b128 v[26:29], v9 offset:10304
	ds_read_b128 v[30:33], v9 offset:10320
	ds_read_b128 v[34:37], v9 offset:8256
	ds_read_b128 v[38:41], v9 offset:8272
	ds_read_b128 v[42:45], v9 offset:8768
	ds_read_b128 v[80:83], v9 offset:8784
	s_mov_b64 exec, vcc
	v_lshlrev_b32_e32 v46, 16, v178
	v_and_b32_e32 v47, 0xffff0000, v178
	v_lshlrev_b32_e32 v84, 16, v179
	v_and_b32_e32 v85, 0xffff0000, v179
	s_waitcnt lgkmcnt(2)
	v_pk_fma_f32 v[26:27], v[34:35], v[46:47], v[26:27]
	v_pk_fma_f32 v[28:29], v[36:37], v[84:85], v[28:29]
	v_lshlrev_b32_e32 v86, 16, v180
	v_and_b32_e32 v87, 0xffff0000, v180
	v_lshlrev_b32_e32 v96, 16, v181
	v_and_b32_e32 v97, 0xffff0000, v181
	v_pk_fma_f32 v[30:31], v[38:39], v[86:87], v[30:31]
	v_pk_fma_f32 v[32:33], v[40:41], v[96:97], v[32:33]
	s_mov_b64 exec, -1
	ds_read_b128 v[34:37], v9 offset:9280
	ds_read_b128 v[38:41], v9 offset:9296
	s_mov_b64 exec, s[0:1]
	v_lshlrev_b32_e32 v46, 16, v182
	v_and_b32_e32 v47, 0xffff0000, v182
	v_lshlrev_b32_e32 v84, 16, v183
	v_and_b32_e32 v85, 0xffff0000, v183
	s_waitcnt lgkmcnt(2)
	v_pk_fma_f32 v[26:27], v[42:43], v[46:47], v[26:27]
	v_pk_fma_f32 v[28:29], v[44:45], v[84:85], v[28:29]
	v_lshlrev_b32_e32 v86, 16, v184
	v_and_b32_e32 v87, 0xffff0000, v184
	v_lshlrev_b32_e32 v96, 16, v185
	v_and_b32_e32 v97, 0xffff0000, v185
	v_pk_fma_f32 v[30:31], v[80:81], v[86:87], v[30:31]
	v_pk_fma_f32 v[32:33], v[82:83], v[96:97], v[32:33]
	s_mov_b64 exec, -1
	ds_read_b128 v[42:45], v9 offset:9792
	ds_read_b128 v[80:83], v9 offset:9808
	v_lshlrev_b32_e32 v46, 16, v186
	v_and_b32_e32 v47, 0xffff0000, v186
	v_lshlrev_b32_e32 v84, 16, v187
	v_and_b32_e32 v85, 0xffff0000, v187
	s_waitcnt lgkmcnt(2)
	v_pk_fma_f32 v[26:27], v[34:35], v[46:47], v[26:27]
	v_pk_fma_f32 v[28:29], v[36:37], v[84:85], v[28:29]
	v_lshlrev_b32_e32 v86, 16, v188
	v_and_b32_e32 v87, 0xffff0000, v188
	v_lshlrev_b32_e32 v96, 16, v189
	v_and_b32_e32 v97, 0xffff0000, v189
	v_pk_fma_f32 v[30:31], v[38:39], v[86:87], v[30:31]
	v_pk_fma_f32 v[32:33], v[40:41], v[96:97], v[32:33]
	s_mov_b64 exec, s[4:5]
	v_lshlrev_b32_e32 v46, 16, v190
	v_and_b32_e32 v47, 0xffff0000, v190
	v_lshlrev_b32_e32 v84, 16, v191
	v_and_b32_e32 v85, 0xffff0000, v191
	s_waitcnt lgkmcnt(0)
	v_pk_fma_f32 v[26:27], v[42:43], v[46:47], v[26:27]
	v_pk_fma_f32 v[28:29], v[44:45], v[84:85], v[28:29]
	v_lshlrev_b32_e32 v86, 16, v192
	v_and_b32_e32 v87, 0xffff0000, v192
	v_lshlrev_b32_e32 v96, 16, v193
	v_and_b32_e32 v97, 0xffff0000, v193
	v_pk_fma_f32 v[30:31], v[80:81], v[86:87], v[30:31]
	v_pk_fma_f32 v[32:33], v[82:83], v[96:97], v[32:33]
	s_mov_b64 exec, -1
	v_cvt_pk_bf16_f32 v52, v26, v27
	v_cvt_pk_bf16_f32 v53, v28, v29
	v_cvt_pk_bf16_f32 v54, v30, v31
	v_cvt_pk_bf16_f32 v55, v32, v33
	s_waitcnt lgkmcnt(3)
	s_waitcnt lgkmcnt(1)
	s_waitcnt lgkmcnt(0)
	s_nop 0
	global_load_dwordx4 v[178:181], v[0:1], off offset:192
	global_load_dwordx4 v[182:185], v[4:5], off offset:192
	global_load_dwordx4 v[186:189], v[2:3], off offset:192
	global_load_dwordx4 v[190:193], v[6:7], off offset:192
	s_waitcnt vmcnt(7)
	s_waitcnt vmcnt(7)
	s_waitcnt lgkmcnt(3)
	s_waitcnt lgkmcnt(1)
	s_waitcnt lgkmcnt(0)
	s_waitcnt vmcnt(7)
	s_waitcnt vmcnt(7)
	ds_read_b128 v[26:29], v9 offset:10368
	ds_read_b128 v[30:33], v9 offset:10384
	ds_read_b128 v[34:37], v9 offset:8320
	ds_read_b128 v[38:41], v9 offset:8336
	ds_read_b128 v[42:45], v9 offset:8832
	ds_read_b128 v[80:83], v9 offset:8848
	s_mov_b64 exec, vcc
	v_lshlrev_b32_e32 v46, 16, v194
	v_and_b32_e32 v47, 0xffff0000, v194
	v_lshlrev_b32_e32 v84, 16, v195
	v_and_b32_e32 v85, 0xffff0000, v195
	s_waitcnt lgkmcnt(2)
	v_pk_fma_f32 v[26:27], v[34:35], v[46:47], v[26:27]
	v_pk_fma_f32 v[28:29], v[36:37], v[84:85], v[28:29]
	v_lshlrev_b32_e32 v86, 16, v196
	v_and_b32_e32 v87, 0xffff0000, v196
	v_lshlrev_b32_e32 v96, 16, v197
	v_and_b32_e32 v97, 0xffff0000, v197
	v_pk_fma_f32 v[30:31], v[38:39], v[86:87], v[30:31]
	v_pk_fma_f32 v[32:33], v[40:41], v[96:97], v[32:33]
	s_mov_b64 exec, -1
	ds_read_b128 v[34:37], v9 offset:9344
	ds_read_b128 v[38:41], v9 offset:9360
	s_mov_b64 exec, s[0:1]
	v_lshlrev_b32_e32 v46, 16, v198
	v_and_b32_e32 v47, 0xffff0000, v198
	v_lshlrev_b32_e32 v84, 16, v199
	v_and_b32_e32 v85, 0xffff0000, v199
	s_waitcnt lgkmcnt(2)
	v_pk_fma_f32 v[26:27], v[42:43], v[46:47], v[26:27]
	v_pk_fma_f32 v[28:29], v[44:45], v[84:85], v[28:29]
	v_lshlrev_b32_e32 v86, 16, v200
	v_and_b32_e32 v87, 0xffff0000, v200
	v_lshlrev_b32_e32 v96, 16, v201
	v_and_b32_e32 v97, 0xffff0000, v201
	v_pk_fma_f32 v[30:31], v[80:81], v[86:87], v[30:31]
	v_pk_fma_f32 v[32:33], v[82:83], v[96:97], v[32:33]
	s_mov_b64 exec, -1
	ds_read_b128 v[42:45], v9 offset:9856
	ds_read_b128 v[80:83], v9 offset:9872
	v_lshlrev_b32_e32 v46, 16, v202
	v_and_b32_e32 v47, 0xffff0000, v202
	v_lshlrev_b32_e32 v84, 16, v203
	v_and_b32_e32 v85, 0xffff0000, v203
	s_waitcnt lgkmcnt(2)
	v_pk_fma_f32 v[26:27], v[34:35], v[46:47], v[26:27]
	v_pk_fma_f32 v[28:29], v[36:37], v[84:85], v[28:29]
	v_lshlrev_b32_e32 v86, 16, v204
	v_and_b32_e32 v87, 0xffff0000, v204
	v_lshlrev_b32_e32 v96, 16, v205
	v_and_b32_e32 v97, 0xffff0000, v205
	v_pk_fma_f32 v[30:31], v[38:39], v[86:87], v[30:31]
	v_pk_fma_f32 v[32:33], v[40:41], v[96:97], v[32:33]
	s_mov_b64 exec, s[4:5]
	v_lshlrev_b32_e32 v46, 16, v206
	v_and_b32_e32 v47, 0xffff0000, v206
	v_lshlrev_b32_e32 v84, 16, v207
	v_and_b32_e32 v85, 0xffff0000, v207
	s_waitcnt lgkmcnt(0)
	v_pk_fma_f32 v[26:27], v[42:43], v[46:47], v[26:27]
	v_pk_fma_f32 v[28:29], v[44:45], v[84:85], v[28:29]
	v_lshlrev_b32_e32 v86, 16, v208
	v_and_b32_e32 v87, 0xffff0000, v208
	v_lshlrev_b32_e32 v96, 16, v209
	v_and_b32_e32 v97, 0xffff0000, v209
	v_pk_fma_f32 v[30:31], v[80:81], v[86:87], v[30:31]
	v_pk_fma_f32 v[32:33], v[82:83], v[96:97], v[32:33]
	s_mov_b64 exec, -1
	v_cvt_pk_bf16_f32 v56, v26, v27
	v_cvt_pk_bf16_f32 v57, v28, v29
	v_cvt_pk_bf16_f32 v58, v30, v31
	v_cvt_pk_bf16_f32 v59, v32, v33
	s_waitcnt lgkmcnt(3)
	s_waitcnt lgkmcnt(1)
	s_waitcnt lgkmcnt(0)
	s_nop 0
	global_load_dwordx4 v[194:197], v[0:1], off offset:224
	global_load_dwordx4 v[198:201], v[4:5], off offset:224
	global_load_dwordx4 v[202:205], v[2:3], off offset:224
	global_load_dwordx4 v[206:209], v[6:7], off offset:224
	s_waitcnt vmcnt(10)
	s_waitcnt vmcnt(10)
	s_waitcnt lgkmcnt(3)
	s_waitcnt lgkmcnt(1)
	s_waitcnt lgkmcnt(0)
	s_waitcnt vmcnt(10)
	s_waitcnt vmcnt(10)
	ds_read_b128 v[0:3], v9 offset:10432
	ds_read_b128 v[4:7], v9 offset:10448
	ds_read_b128 v[26:29], v9 offset:8384
	ds_read_b128 v[30:33], v9 offset:8400
	ds_read_b128 v[34:37], v9 offset:8896
	ds_read_b128 v[38:41], v9 offset:8912
	s_mov_b64 exec, vcc
	v_lshlrev_b32_e32 v42, 16, v210
	v_and_b32_e32 v43, 0xffff0000, v210
	v_lshlrev_b32_e32 v44, 16, v211
	v_and_b32_e32 v45, 0xffff0000, v211
	s_waitcnt lgkmcnt(2)
	v_pk_fma_f32 v[0:1], v[26:27], v[42:43], v[0:1]
	v_pk_fma_f32 v[2:3], v[28:29], v[44:45], v[2:3]
	v_lshlrev_b32_e32 v46, 16, v212
	v_and_b32_e32 v47, 0xffff0000, v212
	v_lshlrev_b32_e32 v80, 16, v213
	v_and_b32_e32 v81, 0xffff0000, v213
	v_pk_fma_f32 v[4:5], v[30:31], v[46:47], v[4:5]
	v_pk_fma_f32 v[6:7], v[32:33], v[80:81], v[6:7]
	s_mov_b64 exec, -1
	ds_read_b128 v[26:29], v9 offset:9408
	ds_read_b128 v[30:33], v9 offset:9424
	s_mov_b64 exec, s[0:1]
	v_lshlrev_b32_e32 v42, 16, v214
	v_and_b32_e32 v43, 0xffff0000, v214
	v_lshlrev_b32_e32 v44, 16, v215
	v_and_b32_e32 v45, 0xffff0000, v215
	s_waitcnt lgkmcnt(2)
	v_pk_fma_f32 v[0:1], v[34:35], v[42:43], v[0:1]
	v_pk_fma_f32 v[2:3], v[36:37], v[44:45], v[2:3]
	v_lshlrev_b32_e32 v46, 16, v216
	v_and_b32_e32 v47, 0xffff0000, v216
	v_lshlrev_b32_e32 v80, 16, v217
	v_and_b32_e32 v81, 0xffff0000, v217
	v_pk_fma_f32 v[4:5], v[38:39], v[46:47], v[4:5]
	v_pk_fma_f32 v[6:7], v[40:41], v[80:81], v[6:7]
	s_mov_b64 exec, -1
	ds_read_b128 v[34:37], v9 offset:9920
	ds_read_b128 v[38:41], v9 offset:9936
	v_lshlrev_b32_e32 v42, 16, v218
	v_and_b32_e32 v43, 0xffff0000, v218
	v_lshlrev_b32_e32 v44, 16, v219
	v_and_b32_e32 v45, 0xffff0000, v219
	s_waitcnt lgkmcnt(2)
	v_pk_fma_f32 v[0:1], v[26:27], v[42:43], v[0:1]
	v_pk_fma_f32 v[2:3], v[28:29], v[44:45], v[2:3]
	v_lshlrev_b32_e32 v46, 16, v220
	v_and_b32_e32 v47, 0xffff0000, v220
	v_lshlrev_b32_e32 v80, 16, v221
	v_and_b32_e32 v81, 0xffff0000, v221
	v_pk_fma_f32 v[4:5], v[30:31], v[46:47], v[4:5]
	v_pk_fma_f32 v[6:7], v[32:33], v[80:81], v[6:7]
	s_mov_b64 exec, s[4:5]
	v_lshlrev_b32_e32 v42, 16, v222
	v_and_b32_e32 v43, 0xffff0000, v222
	v_lshlrev_b32_e32 v44, 16, v223
	v_and_b32_e32 v45, 0xffff0000, v223
	s_waitcnt lgkmcnt(0)
	v_pk_fma_f32 v[0:1], v[34:35], v[42:43], v[0:1]
	v_pk_fma_f32 v[2:3], v[36:37], v[44:45], v[2:3]
	v_lshlrev_b32_e32 v46, 16, v224
	v_and_b32_e32 v47, 0xffff0000, v224
	v_lshlrev_b32_e32 v80, 16, v225
	v_and_b32_e32 v81, 0xffff0000, v225
	v_pk_fma_f32 v[4:5], v[38:39], v[46:47], v[4:5]
	v_pk_fma_f32 v[6:7], v[40:41], v[80:81], v[6:7]
	s_mov_b64 exec, -1
	v_cvt_pk_bf16_f32 v60, v0, v1
	v_cvt_pk_bf16_f32 v61, v2, v3
	v_cvt_pk_bf16_f32 v62, v4, v5
	v_cvt_pk_bf16_f32 v63, v6, v7
	s_waitcnt lgkmcnt(3)
	s_waitcnt lgkmcnt(1)
	s_waitcnt lgkmcnt(0)
	s_nop 0
	s_waitcnt vmcnt(9)
	s_waitcnt vmcnt(9)
	s_waitcnt lgkmcnt(3)
	s_waitcnt lgkmcnt(1)
	s_waitcnt lgkmcnt(0)
	s_waitcnt vmcnt(9)
	s_waitcnt vmcnt(9)
	ds_read_b128 v[0:3], v9 offset:10496
	ds_read_b128 v[4:7], v9 offset:10512
	ds_read_b128 v[26:29], v9 offset:8448
	ds_read_b128 v[30:33], v9 offset:8464
	ds_read_b128 v[34:37], v9 offset:8960
	ds_read_b128 v[38:41], v9 offset:8976
	s_mov_b64 exec, vcc
	v_lshlrev_b32_e32 v42, 16, v226
	v_and_b32_e32 v43, 0xffff0000, v226
	v_lshlrev_b32_e32 v44, 16, v227
	v_and_b32_e32 v45, 0xffff0000, v227
	s_waitcnt lgkmcnt(2)
	v_pk_fma_f32 v[0:1], v[26:27], v[42:43], v[0:1]
	v_pk_fma_f32 v[2:3], v[28:29], v[44:45], v[2:3]
	v_lshlrev_b32_e32 v46, 16, v228
	v_and_b32_e32 v47, 0xffff0000, v228
	v_lshlrev_b32_e32 v80, 16, v229
	v_and_b32_e32 v81, 0xffff0000, v229
	v_pk_fma_f32 v[4:5], v[30:31], v[46:47], v[4:5]
	v_pk_fma_f32 v[6:7], v[32:33], v[80:81], v[6:7]
	s_mov_b64 exec, -1
	ds_read_b128 v[26:29], v9 offset:9472
	ds_read_b128 v[30:33], v9 offset:9488
	s_mov_b64 exec, s[0:1]
	v_lshlrev_b32_e32 v42, 16, v230
	v_and_b32_e32 v43, 0xffff0000, v230
	v_lshlrev_b32_e32 v44, 16, v231
	v_and_b32_e32 v45, 0xffff0000, v231
	s_waitcnt lgkmcnt(2)
	v_pk_fma_f32 v[0:1], v[34:35], v[42:43], v[0:1]
	v_pk_fma_f32 v[2:3], v[36:37], v[44:45], v[2:3]
	v_lshlrev_b32_e32 v46, 16, v232
	v_and_b32_e32 v47, 0xffff0000, v232
	v_lshlrev_b32_e32 v80, 16, v233
	v_and_b32_e32 v81, 0xffff0000, v233
	v_pk_fma_f32 v[4:5], v[38:39], v[46:47], v[4:5]
	v_pk_fma_f32 v[6:7], v[40:41], v[80:81], v[6:7]
	s_mov_b64 exec, -1
	ds_read_b128 v[34:37], v9 offset:9984
	ds_read_b128 v[38:41], v9 offset:10000
	v_lshlrev_b32_e32 v42, 16, v234
	v_and_b32_e32 v43, 0xffff0000, v234
	v_lshlrev_b32_e32 v44, 16, v235
	v_and_b32_e32 v45, 0xffff0000, v235
	s_waitcnt lgkmcnt(2)
	v_pk_fma_f32 v[0:1], v[26:27], v[42:43], v[0:1]
	v_pk_fma_f32 v[2:3], v[28:29], v[44:45], v[2:3]
	v_lshlrev_b32_e32 v46, 16, v236
	v_and_b32_e32 v47, 0xffff0000, v236
	v_lshlrev_b32_e32 v80, 16, v237
	v_and_b32_e32 v81, 0xffff0000, v237
	v_pk_fma_f32 v[4:5], v[30:31], v[46:47], v[4:5]
	v_pk_fma_f32 v[6:7], v[32:33], v[80:81], v[6:7]
	s_mov_b64 exec, s[4:5]
	v_lshlrev_b32_e32 v42, 16, v238
	v_and_b32_e32 v43, 0xffff0000, v238
	v_lshlrev_b32_e32 v44, 16, v239
	v_and_b32_e32 v45, 0xffff0000, v239
	s_waitcnt lgkmcnt(0)
	v_pk_fma_f32 v[0:1], v[34:35], v[42:43], v[0:1]
	v_pk_fma_f32 v[2:3], v[36:37], v[44:45], v[2:3]
	v_lshlrev_b32_e32 v46, 16, v240
	v_and_b32_e32 v47, 0xffff0000, v240
	v_lshlrev_b32_e32 v80, 16, v241
	v_and_b32_e32 v81, 0xffff0000, v241
	v_pk_fma_f32 v[4:5], v[38:39], v[46:47], v[4:5]
	v_pk_fma_f32 v[6:7], v[40:41], v[80:81], v[6:7]
	s_mov_b64 exec, -1
	v_cvt_pk_bf16_f32 v64, v0, v1
	v_cvt_pk_bf16_f32 v65, v2, v3
	v_cvt_pk_bf16_f32 v66, v4, v5
	v_cvt_pk_bf16_f32 v67, v6, v7
	s_waitcnt lgkmcnt(3)
	s_waitcnt lgkmcnt(1)
	s_waitcnt lgkmcnt(0)
	s_nop 0
	s_waitcnt vmcnt(8)
	s_waitcnt vmcnt(8)
	s_waitcnt lgkmcnt(3)
	s_waitcnt lgkmcnt(1)
	s_waitcnt lgkmcnt(0)
	s_waitcnt vmcnt(8)
	s_waitcnt vmcnt(8)
	ds_read_b128 v[0:3], v9 offset:10560
	ds_read_b128 v[4:7], v9 offset:10576
	ds_read_b128 v[26:29], v9 offset:8512
	ds_read_b128 v[30:33], v9 offset:8528
	ds_read_b128 v[34:37], v9 offset:9024
	ds_read_b128 v[38:41], v9 offset:9040
	s_mov_b64 exec, vcc
	v_lshlrev_b32_e32 v42, 16, v242
	v_and_b32_e32 v43, 0xffff0000, v242
	v_lshlrev_b32_e32 v44, 16, v243
	v_and_b32_e32 v45, 0xffff0000, v243
	s_waitcnt lgkmcnt(2)
	v_pk_fma_f32 v[0:1], v[26:27], v[42:43], v[0:1]
	v_pk_fma_f32 v[2:3], v[28:29], v[44:45], v[2:3]
	v_lshlrev_b32_e32 v46, 16, v244
	v_and_b32_e32 v47, 0xffff0000, v244
	v_lshlrev_b32_e32 v80, 16, v245
	v_and_b32_e32 v81, 0xffff0000, v245
	v_pk_fma_f32 v[4:5], v[30:31], v[46:47], v[4:5]
	v_pk_fma_f32 v[6:7], v[32:33], v[80:81], v[6:7]
	s_mov_b64 exec, -1
	ds_read_b128 v[26:29], v9 offset:9536
	ds_read_b128 v[30:33], v9 offset:9552
	s_mov_b64 exec, s[0:1]
	v_lshlrev_b32_e32 v42, 16, v246
	v_and_b32_e32 v43, 0xffff0000, v246
	v_lshlrev_b32_e32 v44, 16, v247
	v_and_b32_e32 v45, 0xffff0000, v247
	s_waitcnt lgkmcnt(2)
	v_pk_fma_f32 v[0:1], v[34:35], v[42:43], v[0:1]
	v_pk_fma_f32 v[2:3], v[36:37], v[44:45], v[2:3]
	v_lshlrev_b32_e32 v46, 16, v248
	v_and_b32_e32 v47, 0xffff0000, v248
	v_lshlrev_b32_e32 v80, 16, v249
	v_and_b32_e32 v81, 0xffff0000, v249
	v_pk_fma_f32 v[4:5], v[38:39], v[46:47], v[4:5]
	v_pk_fma_f32 v[6:7], v[40:41], v[80:81], v[6:7]
	s_mov_b64 exec, -1
	ds_read_b128 v[34:37], v9 offset:10048
	ds_read_b128 v[38:41], v9 offset:10064
	v_lshlrev_b32_e32 v42, 16, v252
	v_and_b32_e32 v43, 0xffff0000, v252
	v_lshlrev_b32_e32 v44, 16, v253
	v_and_b32_e32 v45, 0xffff0000, v253
	s_waitcnt lgkmcnt(2)
	v_pk_fma_f32 v[0:1], v[26:27], v[42:43], v[0:1]
	v_pk_fma_f32 v[2:3], v[28:29], v[44:45], v[2:3]
	v_lshlrev_b32_e32 v46, 16, v254
	v_and_b32_e32 v47, 0xffff0000, v254
	v_lshlrev_b32_e32 v80, 16, v255
	v_and_b32_e32 v81, 0xffff0000, v255
	v_pk_fma_f32 v[4:5], v[30:31], v[46:47], v[4:5]
	v_pk_fma_f32 v[6:7], v[32:33], v[80:81], v[6:7]
	s_mov_b64 exec, s[4:5]
	v_lshlrev_b32_e32 v42, 16, v168
	v_and_b32_e32 v43, 0xffff0000, v168
	v_lshlrev_b32_e32 v44, 16, v169
	v_and_b32_e32 v45, 0xffff0000, v169
	s_waitcnt lgkmcnt(0)
	v_pk_fma_f32 v[0:1], v[34:35], v[42:43], v[0:1]
	v_pk_fma_f32 v[2:3], v[36:37], v[44:45], v[2:3]
	v_lshlrev_b32_e32 v46, 16, v170
	v_and_b32_e32 v47, 0xffff0000, v170
	v_lshlrev_b32_e32 v80, 16, v171
	v_and_b32_e32 v81, 0xffff0000, v171
	v_pk_fma_f32 v[4:5], v[38:39], v[46:47], v[4:5]
	v_pk_fma_f32 v[6:7], v[40:41], v[80:81], v[6:7]
	s_mov_b64 exec, -1
	v_cvt_pk_bf16_f32 v68, v0, v1
	v_cvt_pk_bf16_f32 v69, v2, v3
	v_cvt_pk_bf16_f32 v70, v4, v5
	v_cvt_pk_bf16_f32 v71, v6, v7
	s_waitcnt lgkmcnt(3)
	s_waitcnt lgkmcnt(1)
	s_waitcnt lgkmcnt(0)
	s_nop 0
	s_waitcnt vmcnt(4)
	s_waitcnt vmcnt(4)
	s_waitcnt lgkmcnt(3)
	s_waitcnt lgkmcnt(1)
	s_waitcnt lgkmcnt(0)
	s_waitcnt vmcnt(4)
	s_waitcnt vmcnt(4)
	ds_read_b128 v[0:3], v9 offset:10624
	ds_read_b128 v[4:7], v9 offset:10640
	ds_read_b128 v[26:29], v9 offset:8576
	ds_read_b128 v[30:33], v9 offset:8592
	ds_read_b128 v[34:37], v9 offset:9088
	ds_read_b128 v[38:41], v9 offset:9104
	s_mov_b64 exec, vcc
	v_lshlrev_b32_e32 v42, 16, v178
	v_and_b32_e32 v43, 0xffff0000, v178
	v_lshlrev_b32_e32 v44, 16, v179
	v_and_b32_e32 v45, 0xffff0000, v179
	s_waitcnt lgkmcnt(2)
	v_pk_fma_f32 v[0:1], v[26:27], v[42:43], v[0:1]
	v_pk_fma_f32 v[2:3], v[28:29], v[44:45], v[2:3]
	v_lshlrev_b32_e32 v46, 16, v180
	v_and_b32_e32 v47, 0xffff0000, v180
	v_lshlrev_b32_e32 v80, 16, v181
	v_and_b32_e32 v81, 0xffff0000, v181
	v_pk_fma_f32 v[4:5], v[30:31], v[46:47], v[4:5]
	v_pk_fma_f32 v[6:7], v[32:33], v[80:81], v[6:7]
	s_mov_b64 exec, -1
	ds_read_b128 v[26:29], v9 offset:9600
	ds_read_b128 v[30:33], v9 offset:9616
	s_mov_b64 exec, s[0:1]
	v_lshlrev_b32_e32 v42, 16, v182
	v_and_b32_e32 v43, 0xffff0000, v182
	v_lshlrev_b32_e32 v44, 16, v183
	v_and_b32_e32 v45, 0xffff0000, v183
	s_waitcnt lgkmcnt(2)
	v_pk_fma_f32 v[0:1], v[34:35], v[42:43], v[0:1]
	v_pk_fma_f32 v[2:3], v[36:37], v[44:45], v[2:3]
	v_lshlrev_b32_e32 v46, 16, v184
	v_and_b32_e32 v47, 0xffff0000, v184
	v_lshlrev_b32_e32 v80, 16, v185
	v_and_b32_e32 v81, 0xffff0000, v185
	v_pk_fma_f32 v[4:5], v[38:39], v[46:47], v[4:5]
	v_pk_fma_f32 v[6:7], v[40:41], v[80:81], v[6:7]
	s_mov_b64 exec, -1
	ds_read_b128 v[34:37], v9 offset:10112
	ds_read_b128 v[38:41], v9 offset:10128
	v_lshlrev_b32_e32 v42, 16, v186
	v_and_b32_e32 v43, 0xffff0000, v186
	v_lshlrev_b32_e32 v44, 16, v187
	v_and_b32_e32 v45, 0xffff0000, v187
	s_waitcnt lgkmcnt(2)
	v_pk_fma_f32 v[0:1], v[26:27], v[42:43], v[0:1]
	v_pk_fma_f32 v[2:3], v[28:29], v[44:45], v[2:3]
	v_lshlrev_b32_e32 v46, 16, v188
	v_and_b32_e32 v47, 0xffff0000, v188
	v_lshlrev_b32_e32 v80, 16, v189
	v_and_b32_e32 v81, 0xffff0000, v189
	v_pk_fma_f32 v[4:5], v[30:31], v[46:47], v[4:5]
	v_pk_fma_f32 v[6:7], v[32:33], v[80:81], v[6:7]
	s_mov_b64 exec, s[4:5]
	v_lshlrev_b32_e32 v42, 16, v190
	v_and_b32_e32 v43, 0xffff0000, v190
	v_lshlrev_b32_e32 v44, 16, v191
	v_and_b32_e32 v45, 0xffff0000, v191
	s_waitcnt lgkmcnt(0)
	v_pk_fma_f32 v[0:1], v[34:35], v[42:43], v[0:1]
	v_pk_fma_f32 v[2:3], v[36:37], v[44:45], v[2:3]
	v_lshlrev_b32_e32 v46, 16, v192
	v_and_b32_e32 v47, 0xffff0000, v192
	v_lshlrev_b32_e32 v80, 16, v193
	v_and_b32_e32 v81, 0xffff0000, v193
	v_pk_fma_f32 v[4:5], v[38:39], v[46:47], v[4:5]
	v_pk_fma_f32 v[6:7], v[40:41], v[80:81], v[6:7]
	s_mov_b64 exec, -1
	v_cvt_pk_bf16_f32 v72, v0, v1
	v_cvt_pk_bf16_f32 v73, v2, v3
	v_cvt_pk_bf16_f32 v74, v4, v5
	v_cvt_pk_bf16_f32 v75, v6, v7
	s_waitcnt lgkmcnt(3)
	s_waitcnt lgkmcnt(1)
	s_waitcnt lgkmcnt(0)
	v_lshlrev_b32_e32 v38, 3, v93
	s_nop 0
	s_nop 0
	v_or_b32_e32 v39, 16, v38
	s_waitcnt vmcnt(0)
	s_waitcnt vmcnt(0)
	s_waitcnt lgkmcnt(3)
	s_waitcnt lgkmcnt(1)
	s_waitcnt lgkmcnt(0)
	s_waitcnt vmcnt(0)
	s_waitcnt vmcnt(0)
	ds_read_b128 v[0:3], v9 offset:10688
	ds_read_b128 v[4:7], v9 offset:10704
	ds_read_b128 v[26:29], v9 offset:8640
	ds_read_b128 v[30:33], v9 offset:8656
	ds_read_b128 v[34:37], v9 offset:9152
	ds_read_b128 v[40:43], v9 offset:9168
	s_mov_b64 exec, vcc
	v_lshlrev_b32_e32 v44, 16, v194
	v_and_b32_e32 v45, 0xffff0000, v194
	v_lshlrev_b32_e32 v46, 16, v195
	v_and_b32_e32 v47, 0xffff0000, v195
	s_waitcnt lgkmcnt(2)
	v_pk_fma_f32 v[0:1], v[26:27], v[44:45], v[0:1]
	v_pk_fma_f32 v[2:3], v[28:29], v[46:47], v[2:3]
	v_lshlrev_b32_e32 v80, 16, v196
	v_and_b32_e32 v81, 0xffff0000, v196
	v_lshlrev_b32_e32 v82, 16, v197
	v_and_b32_e32 v83, 0xffff0000, v197
	v_pk_fma_f32 v[4:5], v[30:31], v[80:81], v[4:5]
	v_pk_fma_f32 v[6:7], v[32:33], v[82:83], v[6:7]
	s_mov_b64 exec, -1
	ds_read_b128 v[26:29], v9 offset:9664
	ds_read_b128 v[30:33], v9 offset:9680
	s_mov_b64 exec, s[0:1]
	v_lshlrev_b32_e32 v44, 16, v198
	v_and_b32_e32 v45, 0xffff0000, v198
	v_lshlrev_b32_e32 v46, 16, v199
	v_and_b32_e32 v47, 0xffff0000, v199
	s_waitcnt lgkmcnt(2)
	v_pk_fma_f32 v[0:1], v[34:35], v[44:45], v[0:1]
	v_pk_fma_f32 v[2:3], v[36:37], v[46:47], v[2:3]
	v_lshlrev_b32_e32 v80, 16, v200
	v_and_b32_e32 v81, 0xffff0000, v200
	v_lshlrev_b32_e32 v82, 16, v201
	v_and_b32_e32 v83, 0xffff0000, v201
	v_pk_fma_f32 v[4:5], v[40:41], v[80:81], v[4:5]
	v_pk_fma_f32 v[6:7], v[42:43], v[82:83], v[6:7]
	s_mov_b64 exec, -1
	ds_read_b128 v[34:37], v9 offset:10176
	ds_read_b128 v[40:43], v9 offset:10192
	v_lshlrev_b32_e32 v44, 16, v202
	v_and_b32_e32 v45, 0xffff0000, v202
	v_lshlrev_b32_e32 v46, 16, v203
	v_and_b32_e32 v47, 0xffff0000, v203
	s_waitcnt lgkmcnt(2)
	v_pk_fma_f32 v[0:1], v[26:27], v[44:45], v[0:1]
	v_pk_fma_f32 v[2:3], v[28:29], v[46:47], v[2:3]
	v_lshlrev_b32_e32 v80, 16, v204
	v_and_b32_e32 v81, 0xffff0000, v204
	v_lshlrev_b32_e32 v82, 16, v205
	v_and_b32_e32 v83, 0xffff0000, v205
	v_pk_fma_f32 v[4:5], v[30:31], v[80:81], v[4:5]
	v_pk_fma_f32 v[6:7], v[32:33], v[82:83], v[6:7]
	s_mov_b64 exec, s[4:5]
	v_lshlrev_b32_e32 v44, 16, v206
	v_and_b32_e32 v45, 0xffff0000, v206
	v_lshlrev_b32_e32 v46, 16, v207
	v_and_b32_e32 v47, 0xffff0000, v207
	s_waitcnt lgkmcnt(0)
	v_pk_fma_f32 v[0:1], v[34:35], v[44:45], v[0:1]
	v_pk_fma_f32 v[2:3], v[36:37], v[46:47], v[2:3]
	v_lshlrev_b32_e32 v80, 16, v208
	v_and_b32_e32 v81, 0xffff0000, v208
	v_lshlrev_b32_e32 v82, 16, v209
	v_and_b32_e32 v83, 0xffff0000, v209
	v_pk_fma_f32 v[4:5], v[40:41], v[80:81], v[4:5]
	v_pk_fma_f32 v[6:7], v[42:43], v[82:83], v[6:7]
	s_mov_b64 exec, -1
	v_cvt_pk_bf16_f32 v76, v0, v1
	v_cvt_pk_bf16_f32 v77, v2, v3
	v_cvt_pk_bf16_f32 v78, v4, v5
	v_cvt_pk_bf16_f32 v79, v6, v7
	s_waitcnt lgkmcnt(3)
	s_waitcnt lgkmcnt(1)
	s_waitcnt lgkmcnt(0)
	v_cmp_eq_u32_e32 vcc, v38, v94
	v_or_b32_e32 v2, 1, v38
	v_cndmask_b32_e32 v0, 0, v134, vcc
	v_or_b32_e32 v1, 2, v38
	v_cmp_eq_u32_e32 vcc, v2, v94
	v_or_b32_e32 v4, 3, v38
	v_or_b32_e32 v3, 4, v38
	v_cndmask_b32_e32 v2, 0, v134, vcc
	v_cmp_eq_u32_e32 vcc, v1, v94
	v_or_b32_e32 v5, 6, v38
	v_or_b32_e32 v6, 5, v38
	v_cndmask_b32_e32 v1, 0, v134, vcc
	v_cmp_eq_u32_e32 vcc, v4, v94
	v_or_b32_e32 v7, 7, v38
	v_or_b32_e32 v11, 17, v38
	v_cndmask_b32_e32 v4, 0, v134, vcc
	v_cmp_eq_u32_e32 vcc, v3, v94
	v_or_b32_e32 v10, 18, v38
	v_or_b32_e32 v13, 19, v38
	v_cndmask_b32_e32 v3, 0, v134, vcc
	v_cmp_eq_u32_e32 vcc, v5, v94
	v_or_b32_e32 v12, 20, v38
	v_or_b32_e32 v14, 22, v38
	v_cndmask_b32_e32 v5, 0, v134, vcc
	v_cmp_eq_u32_e32 vcc, v6, v94
	v_or_b32_e32 v15, 21, v38
	v_or_b32_e32 v16, 23, v38
	v_cndmask_b32_e32 v6, 0, v134, vcc
	v_cmp_eq_u32_e32 vcc, v7, v94
	v_and_b32_e32 v18, 64, v132
	v_xor_b32_e32 v17, 32, v132
	v_cndmask_b32_e32 v7, 0, v134, vcc
	v_cmp_eq_u32_e32 vcc, v39, v94
	v_add_u32_e32 v18, 64, v18
	s_lshl_b32 s4, s62, 8
	v_cndmask_b32_e32 v9, 0, v134, vcc
	v_cmp_eq_u32_e32 vcc, v11, v94
	s_add_i32 s4, s4, 16
	v_cmp_eq_u32_e64 s[0:1], 0, v93
	v_cndmask_b32_e32 v11, 0, v134, vcc
	v_cmp_eq_u32_e32 vcc, v10, v94
	v_lshl_add_u32 v139, v94, 3, s4
	v_perm_b32 v82, v6, v3, s83
	v_cndmask_b32_e32 v10, 0, v134, vcc
	v_cmp_eq_u32_e32 vcc, v13, v94
	v_perm_b32 v81, v4, v1, s83
	v_perm_b32 v83, v7, v5, s83
	v_cndmask_b32_e32 v13, 0, v134, vcc
	v_cmp_eq_u32_e32 vcc, v12, v94
	v_perm_b32 v80, v2, v0, s83
	v_perm_b32 v85, v13, v10, s83
	v_cndmask_b32_e32 v12, 0, v134, vcc
	v_cmp_eq_u32_e32 vcc, v14, v94
	v_perm_b32 v84, v11, v9, s83
	s_nop 0
	v_cndmask_b32_e32 v14, 0, v134, vcc
	v_cmp_eq_u32_e32 vcc, v15, v94
	s_nop 1
	v_cndmask_b32_e32 v15, 0, v134, vcc
	v_cmp_eq_u32_e32 vcc, v16, v94
	v_perm_b32 v86, v15, v12, s83
	s_nop 0
	v_cndmask_b32_e32 v16, 0, v134, vcc
	v_cmp_lt_i32_e32 vcc, v17, v18
	v_perm_b32 v87, v16, v14, s83
	s_nop 0
	v_cndmask_b32_e32 v17, v132, v17, vcc
	v_lshlrev_b32_e32 v140, 2, v17
	v_lshlrev_b32_e32 v175, 2, v91
	global_load_dword v172, v175, s[42:43]
	global_load_dword v173, v175, s[36:37]
	global_load_dword v174, v175, s[40:41]
	s_setprio 1
	v_xad_u32 v148, v88, v8, v95
	ds_read_b128 v[0:3], v148 offset:16384
	ds_read_b128 v[4:7], v148 offset:49152
	s_waitcnt lgkmcnt(1)
	v_mfma_f32_32x32x16_bf16 v[32:47], v[48:51], v[0:3], 0
	v_or_b32_e32 v0, 32, v88
	v_xad_u32 v150, v0, v8, v95
	s_waitcnt lgkmcnt(0)
	v_mfma_f32_32x32x16_bf16 v[16:31], v[48:51], v[4:7], 0
	ds_read_b128 v[0:3], v150 offset:16384
	ds_read_b128 v[4:7], v150 offset:49152
	s_waitcnt lgkmcnt(1)
	v_mfma_f32_32x32x16_bf16 v[32:47], v[52:55], v[0:3], v[32:47]
	v_or_b32_e32 v0, 64, v88
	v_xad_u32 v145, v0, v8, v95
	s_waitcnt lgkmcnt(0)
	v_mfma_f32_32x32x16_bf16 v[16:31], v[52:55], v[4:7], v[16:31]
	ds_read_b128 v[0:3], v145 offset:16384
	ds_read_b128 v[4:7], v145 offset:49152
	s_waitcnt lgkmcnt(1)
	v_mfma_f32_32x32x16_bf16 v[32:47], v[56:59], v[0:3], v[32:47]
	v_or_b32_e32 v0, 0x60, v88
	v_xad_u32 v149, v0, v8, v95
	s_waitcnt lgkmcnt(0)
	v_mfma_f32_32x32x16_bf16 v[16:31], v[56:59], v[4:7], v[16:31]
	ds_read_b128 v[0:3], v149 offset:16384
	ds_read_b128 v[4:7], v149 offset:49152
	s_waitcnt lgkmcnt(1)
	v_mfma_f32_32x32x16_bf16 v[32:47], v[60:63], v[0:3], v[32:47]
	v_or_b32_e32 v0, 0x80, v88
	v_xad_u32 v144, v0, v8, v95
	s_waitcnt lgkmcnt(0)
	v_mfma_f32_32x32x16_bf16 v[16:31], v[60:63], v[4:7], v[16:31]
	ds_read_b128 v[0:3], v144 offset:16384
	ds_read_b128 v[4:7], v144 offset:49152
	s_waitcnt lgkmcnt(1)
	v_mfma_f32_32x32x16_bf16 v[32:47], v[64:67], v[0:3], v[32:47]
	v_or_b32_e32 v0, 0xa0, v88
	v_xad_u32 v147, v0, v8, v95
	s_waitcnt lgkmcnt(0)
	v_mfma_f32_32x32x16_bf16 v[16:31], v[64:67], v[4:7], v[16:31]
	ds_read_b128 v[0:3], v147 offset:16384
	ds_read_b128 v[4:7], v147 offset:49152
	s_waitcnt lgkmcnt(1)
	v_mfma_f32_32x32x16_bf16 v[32:47], v[68:71], v[0:3], v[32:47]
	v_or_b32_e32 v0, 0xc0, v88
	v_xad_u32 v143, v0, v8, v95
	s_waitcnt lgkmcnt(0)
	v_mfma_f32_32x32x16_bf16 v[16:31], v[68:71], v[4:7], v[16:31]
	ds_read_b128 v[0:3], v143 offset:16384
	ds_read_b128 v[4:7], v143 offset:49152
	s_waitcnt lgkmcnt(1)
	v_mfma_f32_32x32x16_bf16 v[32:47], v[72:75], v[0:3], v[32:47]
	v_or_b32_e32 v0, 0xe0, v88
	v_xad_u32 v146, v0, v8, v95
	s_waitcnt lgkmcnt(0)
	v_mfma_f32_32x32x16_bf16 v[16:31], v[72:75], v[4:7], v[16:31]
	ds_read_b128 v[0:3], v146 offset:16384
	ds_read_b128 v[4:7], v146 offset:49152
	s_waitcnt lgkmcnt(1)
	v_mfma_f32_32x32x16_bf16 v[32:47], v[76:79], v[0:3], v[32:47]
	s_waitcnt lgkmcnt(0)
	v_mfma_f32_32x32x16_bf16 v[16:31], v[76:79], v[4:7], v[16:31]
	v_mfma_f32_32x32x16_bf16 v[0:15], v[48:51], v[80:83], 0
	v_mfma_f32_32x32x16_bf16 v[0:15], v[52:55], v[84:87], v[0:15]
	s_setprio 0
	v_lshlrev_b32_e32 v88, 2, v91
	s_waitcnt vmcnt(0)
	ds_read_b32 v251, v167
	v_mul_f32_e32 v97, 0xbfb8aa3b, v173
	v_mul_f32_e32 v96, 0xbfb8aa3b, v174
	v_fmamk_f32 v32, v32, 0xbfb8aa3b, v97
	v_fmamk_f32 v34, v34, 0xbfb8aa3b, v97
	v_fmamk_f32 v33, v33, 0xbfb8aa3b, v97
	v_fmamk_f32 v35, v35, 0xbfb8aa3b, v97
	v_fmamk_f32 v16, v16, 0xbfb8aa3b, v96
	v_fmamk_f32 v17, v17, 0xbfb8aa3b, v96
	v_exp_f32_e32 v32, v32
	v_exp_f32_e32 v34, v34
	v_exp_f32_e32 v33, v33
	v_exp_f32_e32 v107, v35
	v_exp_f32_e32 v91, v16
	v_exp_f32_e32 v98, v17
	v_add_f32_e32 v32, 1.0, v32
	v_add_f32_e32 v108, 1.0, v34
	v_add_f32_e32 v33, 1.0, v33
	v_rcp_f32_e32 v109, v32
	v_rcp_f32_e32 v111, v33
	v_add_f32_e32 v91, 1.0, v91
	v_rcp_f32_e32 v110, v91
	v_add_f32_e32 v98, 1.0, v98
	v_rcp_f32_e32 v112, v98
	v_fmamk_f32 v18, v18, 0xbfb8aa3b, v96
	v_exp_f32_e32 v18, v18
	v_fmamk_f32 v20, v20, 0xbfb8aa3b, v96
	v_add_f32_e32 v18, 1.0, v18
	v_exp_f32_e32 v20, v20
	v_fmamk_f32 v19, v19, 0xbfb8aa3b, v96
	v_exp_f32_e32 v19, v19
	v_fmamk_f32 v21, v21, 0xbfb8aa3b, v96
	s_waitcnt lgkmcnt(0)
	v_mul_f32_e32 v33, 0x3fb8aa3b, v251
	v_mul_f32_e32 v16, v109, v33
	v_exp_f32_e32 v32, v16
	v_mul_f32_e32 v17, v111, v33
	v_exp_f32_e32 v34, v17
	v_rcp_f32_e32 v16, v108
	v_rcp_f32_e32 v17, v18
	v_fma_f32 v18, -v32, v32, 1.0
	v_sqrt_f32_e32 v18, v18
	v_mul_f32_e32 v16, v16, v33
	v_add_f32_e32 v19, 1.0, v19
	v_mul_f32_e32 v18, v110, v18
	v_mul_f32_e32 v18, v0, v18
	v_exp_f32_e32 v0, v16
	v_add_f32_e32 v16, 1.0, v107
	v_rcp_f32_e32 v16, v16
	v_rcp_f32_e32 v19, v19
	v_fma_f32 v91, -v0, v0, 1.0
	v_sqrt_f32_e32 v91, v91
	v_mul_f32_e32 v16, v16, v33
	v_exp_f32_e32 v98, v16
	v_fmamk_f32 v16, v36, 0xbfb8aa3b, v97
	v_exp_f32_e32 v16, v16
	v_mul_f32_e32 v91, v17, v91
	v_add_f32_e32 v17, 1.0, v20
	v_fma_f32 v36, -v98, v98, 1.0
	v_add_f32_e32 v16, 1.0, v16
	v_rcp_f32_e32 v16, v16
	v_sqrt_f32_e32 v36, v36
	v_rcp_f32_e32 v17, v17
	v_mul_f32_e32 v16, v16, v33
	v_exp_f32_e32 v20, v16
	v_fmamk_f32 v16, v37, 0xbfb8aa3b, v97
	v_exp_f32_e32 v16, v16
	v_mul_f32_e32 v36, v19, v36
	v_fma_f32 v19, -v20, v20, 1.0
	v_sqrt_f32_e32 v19, v19
	v_add_f32_e32 v16, 1.0, v16
	v_rcp_f32_e32 v16, v16
	v_exp_f32_e32 v21, v21
	v_mul_f32_e32 v17, v17, v19
	v_mul_f32_e32 v19, v4, v17
	v_mul_f32_e32 v16, v16, v33
	v_exp_f32_e32 v37, v16
	v_fmamk_f32 v16, v38, 0xbfb8aa3b, v97
	v_exp_f32_e32 v16, v16
	v_add_f32_e32 v4, 1.0, v21
	v_fmamk_f32 v21, v22, 0xbfb8aa3b, v96
	v_add_f32_e32 v16, 1.0, v16
	v_rcp_f32_e32 v16, v16
	v_fma_f32 v17, -v37, v37, 1.0
	v_exp_f32_e32 v21, v21
	v_rcp_f32_e32 v4, v4
	v_mul_f32_e32 v16, v16, v33
	v_sqrt_f32_e32 v17, v17
	v_exp_f32_e32 v38, v16
	v_add_f32_e32 v16, 1.0, v21
	v_fmamk_f32 v21, v39, 0xbfb8aa3b, v97
	v_mul_f32_e32 v4, v4, v17
	v_fma_f32 v17, -v38, v38, 1.0
	v_rcp_f32_e32 v16, v16
	v_sqrt_f32_e32 v17, v17
	v_exp_f32_e32 v21, v21
	v_fmamk_f32 v22, v23, 0xbfb8aa3b, v96
	v_mul_f32_e32 v23, v16, v17
	v_add_f32_e32 v16, 1.0, v21
	v_rcp_f32_e32 v16, v16
	v_fmamk_f32 v21, v40, 0xbfb8aa3b, v97
	v_exp_f32_e32 v21, v21
	v_mul_f32_e32 v16, v16, v33
	v_exp_f32_e32 v39, v16
	v_add_f32_e32 v16, 1.0, v21
	v_rcp_f32_e32 v16, v16
	v_exp_f32_e32 v22, v22
	v_fmamk_f32 v21, v24, 0xbfb8aa3b, v96
	v_mul_f32_e32 v16, v16, v33
	v_add_f32_e32 v17, 1.0, v22
	v_fma_f32 v22, -v39, v39, 1.0
	v_sqrt_f32_e32 v24, v22
	v_exp_f32_e32 v22, v16
	v_fmamk_f32 v16, v41, 0xbfb8aa3b, v97
	v_exp_f32_e32 v16, v16
	v_exp_f32_e32 v21, v21
	v_fma_f32 v40, -v22, v22, 1.0
	v_rcp_f32_e32 v17, v17
	v_add_f32_e32 v16, 1.0, v16
	v_rcp_f32_e32 v16, v16
	v_add_f32_e32 v21, 1.0, v21
	v_rcp_f32_e32 v21, v21
	v_sqrt_f32_e32 v40, v40
	v_mul_f32_e32 v16, v16, v33
	v_mul_f32_e32 v24, v17, v24
	v_mul_f32_e32 v17, v21, v40
	v_exp_f32_e32 v40, v16
	v_fmamk_f32 v16, v42, 0xbfb8aa3b, v97
	v_fmamk_f32 v25, v25, 0xbfb8aa3b, v96
	v_exp_f32_e32 v16, v16
	v_exp_f32_e32 v25, v25
	v_fma_f32 v35, -v34, v34, 1.0
	v_sqrt_f32_e32 v35, v35
	v_add_f32_e32 v16, 1.0, v16
	v_add_f32_e32 v21, 1.0, v25
	v_rcp_f32_e32 v16, v16
	v_rcp_f32_e32 v25, v21
	v_fma_f32 v21, -v40, v40, 1.0
	v_sqrt_f32_e32 v41, v21
	v_fmamk_f32 v21, v26, 0xbfb8aa3b, v96
	v_mul_f32_e32 v16, v16, v33
	v_exp_f32_e32 v26, v21
	v_mul_f32_e32 v21, v8, v17
	v_mul_f32_e32 v8, v25, v41
	v_exp_f32_e32 v41, v16
	v_fmamk_f32 v16, v43, 0xbfb8aa3b, v97
	v_exp_f32_e32 v16, v16
	v_add_f32_e32 v17, 1.0, v26
	v_fma_f32 v25, -v41, v41, 1.0
	v_fmamk_f32 v26, v27, 0xbfb8aa3b, v96
	v_add_f32_e32 v16, 1.0, v16
	v_rcp_f32_e32 v16, v16
	v_rcp_f32_e32 v17, v17
	v_sqrt_f32_e32 v25, v25
	v_mul_f32_e32 v16, v16, v33
	v_exp_f32_e32 v26, v26
	v_exp_f32_e32 v99, v16
	v_mul_f32_e32 v100, v17, v25
	v_fmamk_f32 v25, v44, 0xbfb8aa3b, v97
	v_add_f32_e32 v16, 1.0, v26
	v_fmamk_f32 v26, v28, 0xbfb8aa3b, v96
	v_fma_f32 v17, -v99, v99, 1.0
	v_exp_f32_e32 v25, v25
	v_rcp_f32_e32 v16, v16
	v_sqrt_f32_e32 v17, v17
	v_exp_f32_e32 v26, v26
	v_add_f32_e32 v25, 1.0, v25
	v_rcp_f32_e32 v25, v25
	v_mul_f32_e32 v101, v16, v17
	v_add_f32_e32 v16, 1.0, v26
	v_fmamk_f32 v26, v29, 0xbfb8aa3b, v96
	v_exp_f32_e32 v26, v26
	v_rcp_f32_e32 v17, v16
	v_mul_f32_e32 v16, v25, v33
	v_fmamk_f32 v25, v45, 0xbfb8aa3b, v97
	v_exp_f32_e32 v25, v25
	v_add_f32_e32 v26, 1.0, v26
	v_rcp_f32_e32 v42, v26
	v_fmamk_f32 v26, v46, 0xbfb8aa3b, v97
	v_exp_f32_e32 v26, v26
	v_add_f32_e32 v25, 1.0, v25
	v_rcp_f32_e32 v25, v25
	v_fmamk_f32 v27, v30, 0xbfb8aa3b, v96
	v_exp_f32_e32 v27, v27
	v_add_f32_e32 v26, 1.0, v26
	v_rcp_f32_e32 v26, v26
	v_mul_f32_e32 v25, v25, v33
	v_exp_f32_e32 v43, v25
	v_add_f32_e32 v25, 1.0, v27
	v_rcp_f32_e32 v44, v25
	v_mul_f32_e32 v25, v26, v33
	v_fmamk_f32 v26, v47, 0xbfb8aa3b, v97
	v_exp_f32_e32 v26, v26
	v_fmamk_f32 v27, v31, 0xbfb8aa3b, v96
	v_exp_f32_e32 v27, v27
	v_add_f32_e32 v26, 1.0, v26
	v_rcp_f32_e32 v26, v26
	v_exp_f32_e32 v16, v16
	v_fmac_f32_e32 v18, 0, v32
	v_mul_f32_e32 v35, v112, v35
	v_exp_f32_e32 v45, v25
	v_add_f32_e32 v25, 1.0, v27
	v_mul_f32_e32 v31, v34, v18
	v_rcp_f32_e32 v46, v25
	v_mul_f32_e32 v25, v26, v33
	v_fmac_f32_e32 v31, v1, v35
	v_mul_f32_e32 v33, v32, v34
	v_mul_f32_e32 v30, v0, v31
	v_mul_f32_e32 v34, v0, v33
	v_fma_f32 v0, -v16, v16, 1.0
	v_sqrt_f32_e32 v1, v0
	v_fmac_f32_e32 v30, v2, v91
	v_fmac_f32_e32 v21, 0, v22
	v_fma_f32 v2, -v43, v43, 1.0
	v_exp_f32_e32 v47, v25
	v_mul_f32_e32 v25, v40, v21
	v_mov_b32_e32 v0, v89
	v_sqrt_f32_e32 v2, v2
	v_fmac_f32_e32 v25, v9, v8
	v_pk_mul_f32 v[8:9], v[16:17], v[0:1]
	v_mul_f32_e32 v29, v98, v30
	v_fmac_f32_e32 v19, 0, v20
	v_fmac_f32_e32 v8, v12, v9
	v_fmac_f32_e32 v29, v3, v36
	v_mul_f32_e32 v28, v37, v19
	v_mov_b32_e32 v3, v8
	v_fmac_f32_e32 v28, v5, v4
	v_pk_mul_f32 v[4:5], v[42:43], v[2:3]
	v_fma_f32 v0, -v45, v45, 1.0
	v_fmac_f32_e32 v5, v13, v4
	v_sqrt_f32_e32 v4, v0
	v_mul_f32_e32 v27, v38, v28
	v_fmac_f32_e32 v27, v6, v23
	v_mul_f32_e32 v26, v39, v27
	v_fmac_f32_e32 v26, v7, v24
	v_pk_mul_f32 v[6:7], v[44:45], v[4:5]
	v_fma_f32 v0, -v47, v47, 1.0
	v_fmac_f32_e32 v7, v14, v6
	v_sqrt_f32_e32 v6, v0
	ds_bpermute_b32 v0, v140, v29
	v_mul_f32_e32 v24, v41, v25
	v_mul_f32_e32 v35, v98, v34
	v_mul_f32_e32 v36, v20, v37
	v_fmac_f32_e32 v24, v10, v100
	v_mul_f32_e32 v37, v38, v36
	v_mul_f32_e32 v23, v99, v24
	ds_bpermute_b32 v13, v140, v35
	v_mul_f32_e32 v38, v39, v37
	v_fmac_f32_e32 v23, v11, v101
	v_pk_mul_f32 v[10:11], v[46:47], v[6:7]
	s_waitcnt lgkmcnt(1)
	v_cndmask_b32_e64 v14, v29, v0, s[0:1]
	v_fmac_f32_e32 v11, v15, v10
	v_cndmask_b32_e64 v10, v0, v29, s[0:1]
	ds_bpermute_b32 v0, v140, v38
	ds_bpermute_b32 v3, v140, v26
	v_mul_f32_e32 v39, v22, v40
	v_mul_f32_e32 v40, v41, v39
	s_waitcnt lgkmcnt(2)
	v_cndmask_b32_e64 v1, v13, v35, s[0:1]
	v_mul_f32_e32 v12, v99, v40
	v_mul_f32_e32 v9, v16, v43
	v_cndmask_b32_e64 v2, v35, v13, s[0:1]
	v_fmac_f32_e32 v10, 0, v1
	v_mul_f32_e32 v4, v45, v9
	v_mul_f32_e32 v15, v35, v13
	v_fmac_f32_e32 v14, v2, v10
	s_waitcnt lgkmcnt(1)
	v_cndmask_b32_e64 v1, v0, v38, s[0:1]
	s_waitcnt lgkmcnt(0)
	v_cndmask_b32_e64 v17, v3, v26, s[0:1]
	v_cndmask_b32_e64 v41, v26, v3, s[0:1]
	ds_bpermute_b32 v2, v140, v12
	ds_bpermute_b32 v3, v140, v23
	v_mul_f32_e32 v6, v47, v4
	v_cndmask_b32_e64 v0, v38, v0, s[0:1]
	v_mul_f32_e32 v42, v15, v1
	v_fmac_f32_e32 v17, v1, v14
	v_mul_f32_e32 v43, v0, v42
	v_fmac_f32_e32 v41, v0, v17
	ds_bpermute_b32 v1, v140, v6
	ds_bpermute_b32 v0, v140, v11
	s_waitcnt lgkmcnt(3)
	v_cndmask_b32_e64 v47, v2, v12, s[0:1]
	s_waitcnt lgkmcnt(2)
	v_cndmask_b32_e64 v44, v3, v23, s[0:1]
	v_cndmask_b32_e64 v2, v12, v2, s[0:1]
	v_cndmask_b32_e64 v45, v23, v3, s[0:1]
	v_mul_f32_e32 v46, v47, v43
	v_fmac_f32_e32 v44, v47, v41
	v_mul_f32_e32 v47, v2, v46
	v_fmac_f32_e32 v45, v2, v44
	s_waitcnt lgkmcnt(1)
	v_cndmask_b32_e64 v2, v1, v6, s[0:1]
	s_waitcnt lgkmcnt(0)
	v_cndmask_b32_e64 v91, v0, v11, s[0:1]
	v_mul_f32_e32 v96, v2, v47
	v_fmac_f32_e32 v91, v2, v45
	s_and_saveexec_b64 s[4:5], s[0:1]
	v_mul_f32_e32 v3, v91, v1
	v_mul_f32_e32 v2, v96, v1
	v_add_f32_e32 v3, v3, v0
	ds_write_b64 v139, v[2:3]
	s_or_b64 exec, exec, s[4:5]
	s_cmp_gt_i32 s62, 0
	s_cselect_b64 s[12:13], -1, 0
	s_cmp_lt_i32 s62, 1
	v_mul_i32_i24_e32 v141, 0xffffff08, v94
	s_waitcnt lgkmcnt(0)
	s_barrier
	s_cbranch_scc1 .LBB0_327
	s_cmp_lt_u32 s62, 8
	s_cbranch_scc1 .LBB0_328
	v_add_u32_e32 v95, v95, v141
	s_and_b32 s4, s62, 0x7ffffff8
	v_mov_b32_e32 v0, 1.0
	v_mov_b32_e32 v3, 0
	s_mov_b32 s5, 0
